# RG staging loads issued together; barrier census loads issued together; write-through stores in prologue and conv
# speedup vs baseline: 1.0158x; 1.0158x over previous
; __device__ __forceinline__ unsigned xb_ld(unsigned* p)              { return __hip_atomic_load(p, __ATOMIC_RELAXED, __HIP_MEMORY_SCOPE_AGENT); }
; __device__ __forceinline__ void xcd_barrier_complete(unsigned* bar, unsigned x, unsigned& nloc, unsigned& nx) {
;     ...
;     unsigned sum, cnt, mine, sp = 0u;
;     for (;;) {
;         sum = 0u; cnt = 0u; mine = 0u;
; #pragma unroll
;         for (unsigned j = 0; j < 16; ++j) { const unsigned c = xb_ld(&bar[XB_XCNT(j)]); sum += c; cnt += (c > 0u) ? 1u : 0u; mine = (j == x) ? c : mine; }
;         if (sum == G) break;
.LBB0_26:
	v_readlane_b32 s6, v252, 16
	v_readlane_b32 s7, v252, 17
	s_waitcnt lgkmcnt(0)
	global_load_dword v0, v85, s[84:85] sc1
	v_readlane_b32 s5, v254, 9
	s_mov_b64 s[30:31], -1
	s_mov_b64 s[34:35], -1
	global_load_dword v1, v85, s[6:7] sc1
	v_readlane_b32 s6, v252, 18
	v_readlane_b32 s7, v252, 19
	s_nop 4
	global_load_dword v2, v85, s[6:7] sc1
	v_readlane_b32 s6, v252, 20
	v_readlane_b32 s7, v252, 21
	s_nop 4
	global_load_dword v3, v85, s[6:7] sc1
	v_readlane_b32 s6, v252, 22
	v_readlane_b32 s7, v252, 23
	s_nop 4
	global_load_dword v4, v85, s[6:7] sc1
	v_readlane_b32 s6, v252, 24
	v_readlane_b32 s7, v252, 25
	s_nop 4
	global_load_dword v5, v85, s[6:7] sc1
	v_readlane_b32 s6, v252, 26
	v_readlane_b32 s7, v252, 27
	s_nop 4
	global_load_dword v6, v85, s[6:7] sc1
	v_readlane_b32 s6, v252, 28
	v_readlane_b32 s7, v252, 29
	s_nop 4
	global_load_dword v7, v85, s[6:7] sc1
	v_readlane_b32 s6, v252, 30
	v_readlane_b32 s7, v252, 31
	s_nop 4
	global_load_dword v8, v85, s[6:7] sc1
	v_readlane_b32 s6, v252, 32
	v_readlane_b32 s7, v252, 33
	s_nop 4
	global_load_dword v9, v85, s[6:7] sc1
	v_readlane_b32 s6, v252, 34
	v_readlane_b32 s7, v252, 35
	s_nop 4
	global_load_dword v10, v85, s[6:7] sc1
	v_readlane_b32 s6, v252, 36
	v_readlane_b32 s7, v252, 37
	s_nop 4
	global_load_dword v11, v85, s[6:7] sc1
	v_readlane_b32 s6, v252, 38
	v_readlane_b32 s7, v252, 39
	s_nop 4
	global_load_dword v12, v85, s[6:7] sc1
	v_readlane_b32 s6, v252, 40
	v_readlane_b32 s7, v252, 41
	s_nop 4
	global_load_dword v13, v85, s[6:7] sc1
	v_readlane_b32 s6, v252, 42
	v_readlane_b32 s7, v252, 43
	s_nop 4
	global_load_dword v14, v85, s[6:7] sc1
	v_readlane_b32 s6, v252, 44
	v_readlane_b32 s7, v252, 45
	s_nop 4
	global_load_dword v15, v85, s[6:7] sc1
	s_waitcnt vmcnt(0)
	v_add_u32_e32 v16, v1, v0
	v_add_u32_e32 v16, v16, v2
	v_add_u32_e32 v16, v16, v3
	v_add_u32_e32 v16, v16, v4
	v_add_u32_e32 v16, v16, v5
	v_add_u32_e32 v16, v16, v6
	v_add_u32_e32 v16, v16, v7
	v_add_u32_e32 v16, v16, v8
	v_add_u32_e32 v16, v16, v9
	v_add_u32_e32 v16, v16, v10
	v_add_u32_e32 v16, v16, v11
	v_add_u32_e32 v16, v16, v12
	v_add_u32_e32 v16, v16, v13
	v_add_u32_e32 v16, v16, v14
	v_add_u32_e32 v16, v16, v15
	v_cmp_eq_u32_e32 vcc, s5, v16
	s_cbranch_vccnz .LBB0_25
	s_and_b32 s5, s4, 0xff
	s_cmp_eq_u32 s5, 0
	s_mov_b64 s[36:37], -1
	s_sleep 1
	s_cbranch_scc0 .LBB0_30
	global_load_dword v16, v85, s[80:81] sc1
	s_waitcnt vmcnt(0)
	v_cmp_eq_u32_e32 vcc, 0, v16
	s_cbranch_vccnz .LBB0_32
	s_mov_b64 s[36:37], 0

; __device__ __forceinline__ unsigned cvtpk(float lo, float hi) { return pg8::cvt_pk_bf16(lo, hi); }
; __device__ __forceinline__ float bflo(unsigned w) { return __uint_as_float(w << 16); }
; __device__ __forceinline__ float bfhi(unsigned w) { return __uint_as_float(w & 0xffff0000u); }
; __device__ __forceinline__ float gelu_tanh(float x) { const float y = x * (1.0f + 0.044715f * x * x); return x * rcp(1.0f + ex2(-2.0f * 0.7978845608028654f * LOG2E * y)); }
; __device__ __forceinline__ void convgelu_phase(const bf16* __restrict__ Z, const float* __restrict__ cw, const float* __restrict__ cb, bf16* __restrict__ H, int G, const int tid_in) {
;     ...
;         for (int n4 = 0; n4 < CG_ROWS; n4 += 4) {
;             v4u gq[4], uq[4];
; #pragma unroll
;             for (int i = 0; i < 4; ++i) { gq[i] = *(const v4u*)(zp + (size_t)(n4 + i) * FF2); uq[i] = *(const v4u*)(zp + (size_t)(n4 + i) * FF2 + FF); }
; #pragma unroll
;             for (int i = 0; i < 4; ++i) { const v4u g0 = gq[i], u0 = uq[i];
;                 float o[8];
; #pragma unroll
;                 for (int e = 0; e < 4; ++e) {
;                     const float ga = bg[2 * e] + wg[0][2 * e] * bflo(g2[e]) + wg[1][2 * e] * bflo(g1[e]) + wg[2][2 * e] * bflo(g0[e]);
;                     const float gb = bg[2 * e + 1] + wg[0][2 * e + 1] * bfhi(g2[e]) + wg[1][2 * e + 1] * bfhi(g1[e]) + wg[2][2 * e + 1] * bfhi(g0[e]);
;                     const float ua = bu[2 * e] + wu[0][2 * e] * bflo(u2[e]) + wu[1][2 * e] * bflo(u1[e]) + wu[2][2 * e] * bflo(u0[e]);
;                     const float ub = bu[2 * e + 1] + wu[0][2 * e + 1] * bfhi(u2[e]) + wu[1][2 * e + 1] * bfhi(u1[e]) + wu[2][2 * e + 1] * bfhi(u0[e]);
;                     o[2 * e] = gelu_tanh(ga) * ua; o[2 * e + 1] = gelu_tanh(gb) * ub;
;                 }
;                 v4u w; w.x = cvtpk(o[0], o[1]); w.y = cvtpk(o[2], o[3]); w.z = cvtpk(o[4], o[5]); w.w = cvtpk(o[6], o[7]);
;                 *(v4u*)(hp + (size_t)(n4 + i) * FF) = w;
;                 g2 = g1; g1 = g0; u2 = u1; u1 = u0; }
.LBB0_102:
	v_lshl_add_u64 v[64:65], v[118:119], 0, v[114:115]
	v_add_co_u32_e32 v66, vcc, 0x2cc00000, v64
	s_waitcnt vmcnt(3)
	v_lshlrev_b32_e32 v120, 16, v86
	v_addc_co_u32_e32 v67, vcc, 0, v65, vcc
	global_load_dwordx4 v[110:113], v[66:67], off
	v_add_co_u32_e32 v66, vcc, 0x2cc02000, v64
	v_and_b32_e32 v121, 0xffff0000, v86
	s_nop 0
	v_addc_co_u32_e32 v67, vcc, 0, v65, vcc
	global_load_dwordx4 v[106:109], v[66:67], off offset:3072
	s_waitcnt vmcnt(4)
	v_pk_fma_f32 v[120:121], v[4:5], v[120:121], v[52:53]
	v_lshlrev_b32_e32 v124, 16, v80
	v_and_b32_e32 v125, 0xffff0000, v80
	v_pk_fma_f32 v[122:123], v[20:21], v[124:125], v[120:121]
	v_add_co_u32_e32 v66, vcc, 0x2cc05000, v64
	s_waitcnt vmcnt(2)
	v_lshlrev_b32_e32 v126, 16, v94
	v_addc_co_u32_e32 v67, vcc, 0, v65, vcc
	v_and_b32_e32 v127, 0xffff0000, v94
	global_load_dwordx4 v[102:105], v[66:67], off offset:2048
	v_lshlrev_b32_e32 v86, 16, v87
	v_and_b32_e32 v87, 0xffff0000, v87
	v_pk_fma_f32 v[86:87], v[6:7], v[86:87], v[54:55]
	v_add_co_u32_e32 v66, vcc, 0x2cc08000, v64
	v_lshlrev_b32_e32 v134, 16, v82
	s_nop 0
	v_addc_co_u32_e32 v67, vcc, 0, v65, vcc
	global_load_dwordx4 v[98:101], v[66:67], off offset:1024
	v_and_b32_e32 v135, 0xffff0000, v82
	v_lshlrev_b32_e32 v144, 16, v83
	v_and_b32_e32 v145, 0xffff0000, v83
	v_lshlrev_b32_e32 v136, 16, v96
	v_and_b32_e32 v137, 0xffff0000, v96
	v_add_co_u32_e32 v66, vcc, 0x2cc0b000, v64
	v_lshlrev_b32_e32 v146, 16, v97
	s_nop 0
	v_addc_co_u32_e32 v67, vcc, 0, v65, vcc
	v_and_b32_e32 v147, 0xffff0000, v97
	global_load_dwordx4 v[72:75], v[66:67], off
	v_add_co_u32_e32 v66, vcc, 0x2cc0d000, v64
	s_mov_b32 s4, 0x37c00000
	s_nop 0
	v_addc_co_u32_e32 v67, vcc, 0, v65, vcc
	global_load_dwordx4 v[68:71], v[66:67], off offset:3072
	v_add_co_u32_e32 v66, vcc, 0x2cc10000, v64
	s_add_i32 s28, s28, 4
	s_nop 0
	v_addc_co_u32_e32 v67, vcc, 0, v65, vcc
	v_add_co_u32_e32 v64, vcc, 0x2cc13000, v64
	global_load_dwordx4 v[76:79], v[66:67], off offset:2048
	s_nop 0
	v_addc_co_u32_e32 v65, vcc, 0, v65, vcc
	global_load_dwordx4 v[64:67], v[64:65], off offset:1024
	s_cmp_gt_u32 s28, 11
	s_waitcnt vmcnt(7)
	v_lshlrev_b32_e32 v120, 16, v110
	v_and_b32_e32 v121, 0xffff0000, v110
	v_pk_fma_f32 v[128:129], v[36:37], v[120:121], v[122:123]
	v_lshlrev_b32_e32 v122, 16, v90
	v_mul_f32_e32 v80, 0x3d372713, v128
	v_fma_f32 v80, v128, v80, 1.0
	v_mul_f32_e32 v80, v128, v80
	v_mul_f32_e32 v80, 0xc0135761, v80
	v_exp_f32_e32 v80, v80
	v_and_b32_e32 v123, 0xffff0000, v90
	v_pk_fma_f32 v[122:123], v[12:13], v[122:123], v[60:61]
	v_lshlrev_b32_e32 v110, 16, v95
	v_add_f32_e32 v80, 1.0, v80
	v_rcp_f32_e32 v132, v80
	v_mul_f32_e32 v80, 0x3d372713, v129
	v_fma_f32 v80, v129, v80, 1.0
	v_mul_f32_e32 v80, v129, v80
	v_mul_f32_e32 v80, 0xc0135761, v80
	v_exp_f32_e32 v80, v80
	v_pk_fma_f32 v[130:131], v[28:29], v[126:127], v[122:123]
	s_waitcnt vmcnt(6)
	v_lshlrev_b32_e32 v122, 16, v106
	v_and_b32_e32 v123, 0xffff0000, v106
	v_add_f32_e32 v80, 1.0, v80
	v_rcp_f32_e32 v133, v80
	v_pk_fma_f32 v[130:131], v[44:45], v[122:123], v[130:131]
	v_lshlrev_b32_e32 v80, 16, v111
	v_pk_mul_f32 v[128:129], v[128:129], v[132:133]
	s_nop 0
	v_pk_mul_f32 v[130:131], v[130:131], v[128:129]
	v_lshlrev_b32_e32 v128, 16, v81
	v_and_b32_e32 v129, 0xffff0000, v81
	v_pk_fma_f32 v[86:87], v[22:23], v[128:129], v[86:87]
	v_and_b32_e32 v81, 0xffff0000, v111
	v_pk_fma_f32 v[132:133], v[38:39], v[80:81], v[86:87]
	v_and_b32_e32 v111, 0xffff0000, v95
	v_mul_f32_e32 v84, 0x3d372713, v132
	v_fma_f32 v84, v132, v84, 1.0
	v_mul_f32_e32 v84, v132, v84
	v_mul_f32_e32 v84, 0xc0135761, v84
	v_exp_f32_e32 v84, v84
	v_lshlrev_b32_e32 v86, 16, v91
	v_and_b32_e32 v87, 0xffff0000, v91
	v_pk_fma_f32 v[86:87], v[14:15], v[86:87], v[62:63]
	v_add_f32_e32 v84, 1.0, v84
	v_rcp_f32_e32 v94, v84
	v_mul_f32_e32 v84, 0x3d372713, v133
	v_fma_f32 v84, v133, v84, 1.0
	v_mul_f32_e32 v84, v133, v84
	v_mul_f32_e32 v84, 0xc0135761, v84
	v_exp_f32_e32 v84, v84
	v_pk_fma_f32 v[90:91], v[30:31], v[110:111], v[86:87]
	v_lshlrev_b32_e32 v86, 16, v107
	v_and_b32_e32 v87, 0xffff0000, v107
	v_add_f32_e32 v84, 1.0, v84
	v_rcp_f32_e32 v95, v84
	v_pk_fma_f32 v[90:91], v[46:47], v[86:87], v[90:91]
	v_pk_mul_f32 v[94:95], v[132:133], v[94:95]
	s_nop 0
	v_pk_mul_f32 v[106:107], v[90:91], v[94:95]
	v_lshlrev_b32_e32 v90, 16, v88
	v_and_b32_e32 v91, 0xffff0000, v88
	v_pk_fma_f32 v[90:91], v[0:1], v[90:91], v[48:49]
	v_lshlrev_b32_e32 v88, 16, v89
	v_pk_fma_f32 v[94:95], v[16:17], v[134:135], v[90:91]
	v_lshlrev_b32_e32 v90, 16, v112
	v_and_b32_e32 v91, 0xffff0000, v112
	v_pk_fma_f32 v[132:133], v[32:33], v[90:91], v[94:95]
	v_and_b32_e32 v89, 0xffff0000, v89
	v_mul_f32_e32 v82, 0x3d372713, v132
	v_fma_f32 v82, v132, v82, 1.0
	v_mul_f32_e32 v82, v132, v82
	v_mul_f32_e32 v82, 0xc0135761, v82
	v_exp_f32_e32 v82, v82
	v_pk_fma_f32 v[88:89], v[2:3], v[88:89], v[50:51]
	v_lshlrev_b32_e32 v94, 16, v92
	v_and_b32_e32 v95, 0xffff0000, v92
	v_add_f32_e32 v82, 1.0, v82
	v_rcp_f32_e32 v142, v82
	v_mul_f32_e32 v82, 0x3d372713, v133
	v_fma_f32 v82, v133, v82, 1.0
	v_mul_f32_e32 v82, v133, v82
	v_mul_f32_e32 v82, 0xc0135761, v82
	v_exp_f32_e32 v82, v82
	v_pk_fma_f32 v[94:95], v[8:9], v[94:95], v[56:57]
	v_lshlrev_b32_e32 v92, 16, v93
	v_pk_fma_f32 v[140:141], v[24:25], v[136:137], v[94:95]
	v_add_f32_e32 v82, 1.0, v82
	v_rcp_f32_e32 v143, v82
	v_pk_fma_f32 v[82:83], v[18:19], v[144:145], v[88:89]
	v_lshlrev_b32_e32 v88, 16, v113
	v_and_b32_e32 v89, 0xffff0000, v113
	v_pk_fma_f32 v[82:83], v[34:35], v[88:89], v[82:83]
	v_lshlrev_b32_e32 v94, 16, v108
	v_mul_f32_e32 v84, 0x3d372713, v82
	v_fma_f32 v84, v82, v84, 1.0
	v_mul_f32_e32 v84, v82, v84
	v_mul_f32_e32 v84, 0xc0135761, v84
	v_exp_f32_e32 v84, v84
	v_and_b32_e32 v95, 0xffff0000, v108
	v_and_b32_e32 v93, 0xffff0000, v93
	v_pk_fma_f32 v[140:141], v[40:41], v[94:95], v[140:141]
	v_add_f32_e32 v84, 1.0, v84
	v_rcp_f32_e32 v96, v84
	v_mul_f32_e32 v84, 0x3d372713, v83
	v_fma_f32 v84, v83, v84, 1.0
	v_mul_f32_e32 v84, v83, v84
	v_mul_f32_e32 v84, 0xc0135761, v84
	v_exp_f32_e32 v84, v84
	v_pk_mul_f32 v[132:133], v[132:133], v[142:143]
	v_pk_fma_f32 v[92:93], v[10:11], v[92:93], v[58:59]
	v_pk_mul_f32 v[142:143], v[140:141], v[132:133]
	v_add_f32_e32 v84, 1.0, v84
	v_rcp_f32_e32 v97, v84
	v_pk_fma_f32 v[92:93], v[26:27], v[146:147], v[92:93]
	v_lshlrev_b32_e32 v132, 16, v109
	v_and_b32_e32 v133, 0xffff0000, v109
	v_pk_fma_f32 v[92:93], v[42:43], v[132:133], v[92:93]
	v_pk_mul_f32 v[82:83], v[82:83], v[96:97]
	v_cvt_pk_bf16_f32 v142, v142, v143
	v_pk_mul_f32 v[82:83], v[92:93], v[82:83]
	v_cvt_pk_bf16_f32 v140, v130, v131
	v_cvt_pk_bf16_f32 v143, v82, v83
	v_lshl_add_u64 v[82:83], v[116:117], 0, v[114:115]
	v_add_co_u32_e32 v92, vcc, s4, v82
	v_cvt_pk_bf16_f32 v141, v106, v107
	s_nop 0
	v_addc_co_u32_e32 v93, vcc, 0, v83, vcc
	global_store_dwordx4 v[92:93], v[140:143], off sc1
	v_pk_fma_f32 v[92:93], v[4:5], v[124:125], v[52:53]
	s_waitcnt vmcnt(6)
; __device__ __forceinline__ unsigned cvtpk(float lo, float hi) { return pg8::cvt_pk_bf16(lo, hi); }
; __device__ __forceinline__ float bflo(unsigned w) { return __uint_as_float(w << 16); }
; __device__ __forceinline__ float bfhi(unsigned w) { return __uint_as_float(w & 0xffff0000u); }
; __device__ __forceinline__ float gelu_tanh(float x) { const float y = x * (1.0f + 0.044715f * x * x); return x * rcp(1.0f + ex2(-2.0f * 0.7978845608028654f * LOG2E * y)); }
; __device__ __forceinline__ void convgelu_phase(const bf16* __restrict__ Z, const float* __restrict__ cw, const float* __restrict__ cb, bf16* __restrict__ H, int G, const int tid_in) {
;     ...
;         for (int n4 = 0; n4 < CG_ROWS; n4 += 4) {
;             v4u gq[4], uq[4];
; #pragma unroll
;             for (int i = 0; i < 4; ++i) { gq[i] = *(const v4u*)(zp + (size_t)(n4 + i) * FF2); uq[i] = *(const v4u*)(zp + (size_t)(n4 + i) * FF2 + FF); }
; #pragma unroll
;             for (int i = 0; i < 4; ++i) { const v4u g0 = gq[i], u0 = uq[i];
;                 float o[8];
; #pragma unroll
;                 for (int e = 0; e < 4; ++e) {
;                     const float ga = bg[2 * e] + wg[0][2 * e] * bflo(g2[e]) + wg[1][2 * e] * bflo(g1[e]) + wg[2][2 * e] * bflo(g0[e]);
;                     const float gb = bg[2 * e + 1] + wg[0][2 * e + 1] * bfhi(g2[e]) + wg[1][2 * e + 1] * bfhi(g1[e]) + wg[2][2 * e + 1] * bfhi(g0[e]);
;                     const float ua = bu[2 * e] + wu[0][2 * e] * bflo(u2[e]) + wu[1][2 * e] * bflo(u1[e]) + wu[2][2 * e] * bflo(u0[e]);
;                     const float ub = bu[2 * e + 1] + wu[0][2 * e + 1] * bfhi(u2[e]) + wu[1][2 * e + 1] * bfhi(u1[e]) + wu[2][2 * e + 1] * bfhi(u0[e]);
;                     o[2 * e] = gelu_tanh(ga) * ua; o[2 * e + 1] = gelu_tanh(gb) * ub;
;                 }
;                 v4u w; w.x = cvtpk(o[0], o[1]); w.y = cvtpk(o[2], o[3]); w.z = cvtpk(o[4], o[5]); w.w = cvtpk(o[6], o[7]);
;                 *(v4u*)(hp + (size_t)(n4 + i) * FF) = w;
;                 g2 = g1; g1 = g0; u2 = u1; u1 = u0; }
	v_lshlrev_b32_e32 v124, 16, v102
	v_pk_fma_f32 v[92:93], v[20:21], v[120:121], v[92:93]
	v_and_b32_e32 v125, 0xffff0000, v102
	v_pk_fma_f32 v[92:93], v[36:37], v[124:125], v[92:93]
	v_pk_fma_f32 v[96:97], v[12:13], v[126:127], v[60:61]
	v_mul_f32_e32 v84, 0x3d372713, v92
	v_fma_f32 v84, v92, v84, 1.0
	v_mul_f32_e32 v84, v92, v84
	v_mul_f32_e32 v84, 0xc0135761, v84
	v_exp_f32_e32 v84, v84
	v_pk_fma_f32 v[96:97], v[28:29], v[122:123], v[96:97]
	s_waitcnt vmcnt(5)
	v_lshlrev_b32_e32 v112, 16, v98
	v_and_b32_e32 v113, 0xffff0000, v98
	v_add_f32_e32 v84, 1.0, v84
	v_rcp_f32_e32 v106, v84
	v_mul_f32_e32 v84, 0x3d372713, v93
	v_fma_f32 v84, v93, v84, 1.0
	v_mul_f32_e32 v84, v93, v84
	v_mul_f32_e32 v84, 0xc0135761, v84
	v_exp_f32_e32 v84, v84
	v_pk_fma_f32 v[96:97], v[44:45], v[112:113], v[96:97]
	v_lshlrev_b32_e32 v108, 16, v103
	v_and_b32_e32 v109, 0xffff0000, v103
	v_add_f32_e32 v84, 1.0, v84
	v_rcp_f32_e32 v107, v84
	v_lshlrev_b32_e32 v102, 16, v104
	v_and_b32_e32 v103, 0xffff0000, v104
	s_mov_b32 s4, 0x37c02000
	v_pk_mul_f32 v[92:93], v[92:93], v[106:107]
	v_lshlrev_b32_e32 v106, 16, v99
	v_pk_mul_f32 v[126:127], v[96:97], v[92:93]
	v_pk_fma_f32 v[92:93], v[6:7], v[128:129], v[54:55]
	v_and_b32_e32 v107, 0xffff0000, v99
	v_pk_fma_f32 v[92:93], v[22:23], v[80:81], v[92:93]
	v_pk_fma_f32 v[96:97], v[14:15], v[110:111], v[62:63]
	v_pk_fma_f32 v[92:93], v[38:39], v[108:109], v[92:93]
	v_pk_fma_f32 v[96:97], v[30:31], v[86:87], v[96:97]
	v_mul_f32_e32 v84, 0x3d372713, v92
	v_fma_f32 v84, v92, v84, 1.0
	v_mul_f32_e32 v84, v92, v84
	v_mul_f32_e32 v84, 0xc0135761, v84
	v_exp_f32_e32 v84, v84
	v_pk_fma_f32 v[96:97], v[46:47], v[106:107], v[96:97]
	v_cvt_pk_bf16_f32 v126, v126, v127
	v_pk_fma_f32 v[80:81], v[6:7], v[80:81], v[54:55]
	v_add_f32_e32 v84, 1.0, v84
	v_rcp_f32_e32 v98, v84
	v_mul_f32_e32 v84, 0x3d372713, v93
	v_fma_f32 v84, v93, v84, 1.0
	v_mul_f32_e32 v84, v93, v84
	v_mul_f32_e32 v84, 0xc0135761, v84
	v_exp_f32_e32 v84, v84
	v_pk_fma_f32 v[80:81], v[22:23], v[108:109], v[80:81]
	v_pk_fma_f32 v[86:87], v[14:15], v[86:87], v[62:63]
	v_add_f32_e32 v84, 1.0, v84
	v_rcp_f32_e32 v99, v84
	v_pk_fma_f32 v[86:87], v[30:31], v[106:107], v[86:87]
	v_pk_mul_f32 v[92:93], v[92:93], v[98:99]
	s_nop 0
	v_pk_mul_f32 v[110:111], v[96:97], v[92:93]
	v_pk_fma_f32 v[92:93], v[0:1], v[134:135], v[48:49]
	v_pk_fma_f32 v[96:97], v[8:9], v[136:137], v[56:57]
	v_pk_fma_f32 v[92:93], v[16:17], v[90:91], v[92:93]
	v_pk_fma_f32 v[96:97], v[24:25], v[94:95], v[96:97]
	v_pk_fma_f32 v[92:93], v[32:33], v[102:103], v[92:93]
	v_lshlrev_b32_e32 v98, 16, v100
	v_mul_f32_e32 v84, 0x3d372713, v92
	v_fma_f32 v84, v92, v84, 1.0
	v_mul_f32_e32 v84, v92, v84
	v_mul_f32_e32 v84, 0xc0135761, v84
	v_exp_f32_e32 v84, v84
	v_and_b32_e32 v99, 0xffff0000, v100
	v_pk_fma_f32 v[96:97], v[40:41], v[98:99], v[96:97]
	v_cvt_pk_bf16_f32 v127, v110, v111
	v_add_f32_e32 v84, 1.0, v84
	v_rcp_f32_e32 v128, v84
	v_mul_f32_e32 v84, 0x3d372713, v93
	v_fma_f32 v84, v93, v84, 1.0
	v_mul_f32_e32 v84, v93, v84
	v_mul_f32_e32 v84, 0xc0135761, v84
	v_exp_f32_e32 v84, v84
	v_pk_fma_f32 v[110:111], v[12:13], v[122:123], v[60:61]
	v_pk_fma_f32 v[94:95], v[8:9], v[94:95], v[56:57]
	v_pk_fma_f32 v[110:111], v[28:29], v[112:113], v[110:111]
	v_add_f32_e32 v84, 1.0, v84
	v_rcp_f32_e32 v129, v84
	v_pk_fma_f32 v[94:95], v[24:25], v[98:99], v[94:95]
	v_pk_mul_f32 v[92:93], v[92:93], v[128:129]
	s_nop 0
	v_pk_mul_f32 v[128:129], v[96:97], v[92:93]
	v_pk_fma_f32 v[92:93], v[2:3], v[144:145], v[50:51]
	v_lshlrev_b32_e32 v96, 16, v105
	v_pk_fma_f32 v[92:93], v[18:19], v[88:89], v[92:93]
	v_and_b32_e32 v97, 0xffff0000, v105
	v_pk_fma_f32 v[104:105], v[34:35], v[96:97], v[92:93]
	v_pk_fma_f32 v[92:93], v[10:11], v[146:147], v[58:59]
	v_mul_f32_e32 v84, 0x3d372713, v104
	v_fma_f32 v84, v104, v84, 1.0
	v_mul_f32_e32 v84, v104, v84
	v_mul_f32_e32 v84, 0xc0135761, v84
	v_exp_f32_e32 v84, v84
	v_pk_fma_f32 v[130:131], v[26:27], v[132:133], v[92:93]
	v_lshlrev_b32_e32 v92, 16, v101
	v_and_b32_e32 v93, 0xffff0000, v101
	v_add_f32_e32 v84, 1.0, v84
	v_pk_fma_f32 v[100:101], v[42:43], v[92:93], v[130:131]
	v_rcp_f32_e32 v130, v84
	v_mul_f32_e32 v84, 0x3d372713, v105
	v_fma_f32 v84, v105, v84, 1.0
	v_mul_f32_e32 v84, v105, v84
	v_mul_f32_e32 v84, 0xc0135761, v84
	v_exp_f32_e32 v84, v84
	v_cvt_pk_bf16_f32 v128, v128, v129
	v_add_f32_e32 v84, 1.0, v84
	v_rcp_f32_e32 v131, v84
	s_nop 0
	v_pk_mul_f32 v[104:105], v[104:105], v[130:131]
	s_nop 0
	v_pk_mul_f32 v[100:101], v[100:101], v[104:105]
	s_waitcnt vmcnt(4)
	v_lshlrev_b32_e32 v104, 16, v72
	v_cvt_pk_bf16_f32 v129, v100, v101
	v_add_co_u32_e32 v100, vcc, s4, v82
	v_and_b32_e32 v105, 0xffff0000, v72
	s_nop 0
	v_addc_co_u32_e32 v101, vcc, 0, v83, vcc
	global_store_dwordx4 v[100:101], v[126:129], off offset:3072 sc1
	v_pk_fma_f32 v[100:101], v[4:5], v[120:121], v[52:53]
	s_waitcnt vmcnt(4)
; __device__ __forceinline__ unsigned cvtpk(float lo, float hi) { return pg8::cvt_pk_bf16(lo, hi); }
; __device__ __forceinline__ float bflo(unsigned w) { return __uint_as_float(w << 16); }
; __device__ __forceinline__ float bfhi(unsigned w) { return __uint_as_float(w & 0xffff0000u); }
; __device__ __forceinline__ float gelu_tanh(float x) { const float y = x * (1.0f + 0.044715f * x * x); return x * rcp(1.0f + ex2(-2.0f * 0.7978845608028654f * LOG2E * y)); }
; __device__ __forceinline__ void convgelu_phase(const bf16* __restrict__ Z, const float* __restrict__ cw, const float* __restrict__ cb, bf16* __restrict__ H, int G, const int tid_in) {
;     ...
;         for (int n4 = 0; n4 < CG_ROWS; n4 += 4) {
;             v4u gq[4], uq[4];
; #pragma unroll
;             for (int i = 0; i < 4; ++i) { gq[i] = *(const v4u*)(zp + (size_t)(n4 + i) * FF2); uq[i] = *(const v4u*)(zp + (size_t)(n4 + i) * FF2 + FF); }
; #pragma unroll
;             for (int i = 0; i < 4; ++i) { const v4u g0 = gq[i], u0 = uq[i];
;                 float o[8];
; #pragma unroll
;                 for (int e = 0; e < 4; ++e) {
;                     const float ga = bg[2 * e] + wg[0][2 * e] * bflo(g2[e]) + wg[1][2 * e] * bflo(g1[e]) + wg[2][2 * e] * bflo(g0[e]);
;                     const float gb = bg[2 * e + 1] + wg[0][2 * e + 1] * bfhi(g2[e]) + wg[1][2 * e + 1] * bfhi(g1[e]) + wg[2][2 * e + 1] * bfhi(g0[e]);
;                     const float ua = bu[2 * e] + wu[0][2 * e] * bflo(u2[e]) + wu[1][2 * e] * bflo(u1[e]) + wu[2][2 * e] * bflo(u0[e]);
;                     const float ub = bu[2 * e + 1] + wu[0][2 * e + 1] * bfhi(u2[e]) + wu[1][2 * e + 1] * bfhi(u1[e]) + wu[2][2 * e + 1] * bfhi(u0[e]);
;                     o[2 * e] = gelu_tanh(ga) * ua; o[2 * e + 1] = gelu_tanh(gb) * ub;
;                 }
;                 v4u w; w.x = cvtpk(o[0], o[1]); w.y = cvtpk(o[2], o[3]); w.z = cvtpk(o[4], o[5]); w.w = cvtpk(o[6], o[7]);
;                 *(v4u*)(hp + (size_t)(n4 + i) * FF) = w;
;                 g2 = g1; g1 = g0; u2 = u1; u1 = u0; }
	v_lshlrev_b32_e32 v120, 16, v68
	v_pk_fma_f32 v[100:101], v[20:21], v[124:125], v[100:101]
	v_and_b32_e32 v121, 0xffff0000, v68
	v_pk_fma_f32 v[100:101], v[36:37], v[104:105], v[100:101]
	v_pk_fma_f32 v[110:111], v[44:45], v[120:121], v[110:111]
	v_mul_f32_e32 v84, 0x3d372713, v100
	v_fma_f32 v84, v100, v84, 1.0
	v_mul_f32_e32 v84, v100, v84
	v_mul_f32_e32 v84, 0xc0135761, v84
	v_exp_f32_e32 v84, v84
	v_lshlrev_b32_e32 v130, 16, v71
	v_and_b32_e32 v131, 0xffff0000, v71
	s_mov_b32 s4, 0x37c05000
	v_add_f32_e32 v84, 1.0, v84
	v_rcp_f32_e32 v122, v84
	v_mul_f32_e32 v84, 0x3d372713, v101
	v_fma_f32 v84, v101, v84, 1.0
	v_mul_f32_e32 v84, v101, v84
	v_mul_f32_e32 v84, 0xc0135761, v84
	v_exp_f32_e32 v84, v84
	s_nop 0
	v_add_f32_e32 v84, 1.0, v84
	v_rcp_f32_e32 v123, v84
	s_nop 0
	v_pk_mul_f32 v[100:101], v[100:101], v[122:123]
	s_nop 0
	v_pk_mul_f32 v[100:101], v[110:111], v[100:101]
	v_lshlrev_b32_e32 v110, 16, v73
	v_and_b32_e32 v111, 0xffff0000, v73
	v_pk_fma_f32 v[80:81], v[38:39], v[110:111], v[80:81]
	v_lshlrev_b32_e32 v122, 16, v69
	v_mul_f32_e32 v84, 0x3d372713, v80
	v_fma_f32 v84, v80, v84, 1.0
	v_mul_f32_e32 v84, v80, v84
	v_mul_f32_e32 v84, 0xc0135761, v84
	v_exp_f32_e32 v84, v84
	v_and_b32_e32 v123, 0xffff0000, v69
	v_pk_fma_f32 v[86:87], v[46:47], v[122:123], v[86:87]
	v_add_f32_e32 v84, 1.0, v84
	v_rcp_f32_e32 v126, v84
	v_mul_f32_e32 v84, 0x3d372713, v81
	v_fma_f32 v84, v81, v84, 1.0
	v_mul_f32_e32 v84, v81, v84
	v_mul_f32_e32 v84, 0xc0135761, v84
	v_exp_f32_e32 v84, v84
	s_nop 0
	v_add_f32_e32 v84, 1.0, v84
	v_rcp_f32_e32 v127, v84
	s_nop 0
	v_pk_mul_f32 v[80:81], v[80:81], v[126:127]
	s_nop 0
	v_pk_mul_f32 v[80:81], v[86:87], v[80:81]
	v_pk_fma_f32 v[86:87], v[0:1], v[90:91], v[48:49]
	v_lshlrev_b32_e32 v90, 16, v74
	v_pk_fma_f32 v[86:87], v[16:17], v[102:103], v[86:87]
	v_and_b32_e32 v91, 0xffff0000, v74
	v_pk_fma_f32 v[86:87], v[32:33], v[90:91], v[86:87]
	v_lshlrev_b32_e32 v126, 16, v70
	v_mul_f32_e32 v84, 0x3d372713, v86
	v_fma_f32 v84, v86, v84, 1.0
	v_mul_f32_e32 v84, v86, v84
	v_mul_f32_e32 v84, 0xc0135761, v84
	v_exp_f32_e32 v84, v84
	v_and_b32_e32 v127, 0xffff0000, v70
	v_pk_fma_f32 v[94:95], v[40:41], v[126:127], v[94:95]
	v_add_f32_e32 v84, 1.0, v84
	v_rcp_f32_e32 v128, v84
	v_mul_f32_e32 v84, 0x3d372713, v87
	v_fma_f32 v84, v87, v84, 1.0
	v_mul_f32_e32 v84, v87, v84
	v_mul_f32_e32 v84, 0xc0135761, v84
	v_exp_f32_e32 v84, v84
	s_nop 0
	v_add_f32_e32 v84, 1.0, v84
	v_rcp_f32_e32 v129, v84
	s_nop 0
	v_pk_mul_f32 v[86:87], v[86:87], v[128:129]
	s_nop 0
	v_pk_mul_f32 v[94:95], v[94:95], v[86:87]
	v_pk_fma_f32 v[86:87], v[2:3], v[88:89], v[50:51]
	v_lshlrev_b32_e32 v128, 16, v75
	v_pk_fma_f32 v[86:87], v[18:19], v[96:97], v[86:87]
	v_and_b32_e32 v129, 0xffff0000, v75
	v_pk_fma_f32 v[86:87], v[34:35], v[128:129], v[86:87]
	v_pk_fma_f32 v[88:89], v[10:11], v[132:133], v[58:59]
	v_mul_f32_e32 v84, 0x3d372713, v86
	v_fma_f32 v84, v86, v84, 1.0
	v_mul_f32_e32 v84, v86, v84
	v_mul_f32_e32 v84, 0xc0135761, v84
	v_exp_f32_e32 v84, v84
	v_pk_fma_f32 v[88:89], v[26:27], v[92:93], v[88:89]
	v_pk_fma_f32 v[92:93], v[10:11], v[92:93], v[58:59]
	v_pk_fma_f32 v[88:89], v[42:43], v[130:131], v[88:89]
	v_add_f32_e32 v84, 1.0, v84
	v_rcp_f32_e32 v132, v84
	v_mul_f32_e32 v84, 0x3d372713, v87
	v_fma_f32 v84, v87, v84, 1.0
	v_mul_f32_e32 v84, v87, v84
	v_mul_f32_e32 v84, 0xc0135761, v84
	v_exp_f32_e32 v84, v84
	v_pk_fma_f32 v[92:93], v[26:27], v[130:131], v[92:93]
	v_add_f32_e32 v84, 1.0, v84
	v_rcp_f32_e32 v133, v84
	s_nop 0
	v_pk_mul_f32 v[86:87], v[86:87], v[132:133]
	s_nop 0
	v_pk_mul_f32 v[132:133], v[88:89], v[86:87]
	v_cvt_pk_bf16_f32 v87, v80, v81
	v_add_co_u32_e32 v80, vcc, s4, v82
	v_cvt_pk_bf16_f32 v86, v100, v101
	v_cvt_pk_bf16_f32 v88, v94, v95
	v_cvt_pk_bf16_f32 v89, v132, v133
	v_addc_co_u32_e32 v81, vcc, 0, v83, vcc
	global_store_dwordx4 v[80:81], v[86:89], off offset:2048 sc1
	v_pk_fma_f32 v[80:81], v[4:5], v[124:125], v[52:53]
	s_waitcnt vmcnt(3)
; __device__ __forceinline__ unsigned cvtpk(float lo, float hi) { return pg8::cvt_pk_bf16(lo, hi); }
; __device__ __forceinline__ float bflo(unsigned w) { return __uint_as_float(w << 16); }
; __device__ __forceinline__ float bfhi(unsigned w) { return __uint_as_float(w & 0xffff0000u); }
; __device__ __forceinline__ float gelu_tanh(float x) { const float y = x * (1.0f + 0.044715f * x * x); return x * rcp(1.0f + ex2(-2.0f * 0.7978845608028654f * LOG2E * y)); }
; __device__ __forceinline__ void convgelu_phase(const bf16* __restrict__ Z, const float* __restrict__ cw, const float* __restrict__ cb, bf16* __restrict__ H, int G, const int tid_in) {
;     ...
;         for (int n4 = 0; n4 < CG_ROWS; n4 += 4) {
;             v4u gq[4], uq[4];
; #pragma unroll
;             for (int i = 0; i < 4; ++i) { gq[i] = *(const v4u*)(zp + (size_t)(n4 + i) * FF2); uq[i] = *(const v4u*)(zp + (size_t)(n4 + i) * FF2 + FF); }
; #pragma unroll
;             for (int i = 0; i < 4; ++i) { const v4u g0 = gq[i], u0 = uq[i];
;                 float o[8];
; #pragma unroll
;                 for (int e = 0; e < 4; ++e) {
;                     const float ga = bg[2 * e] + wg[0][2 * e] * bflo(g2[e]) + wg[1][2 * e] * bflo(g1[e]) + wg[2][2 * e] * bflo(g0[e]);
;                     const float gb = bg[2 * e + 1] + wg[0][2 * e + 1] * bfhi(g2[e]) + wg[1][2 * e + 1] * bfhi(g1[e]) + wg[2][2 * e + 1] * bfhi(g0[e]);
;                     const float ua = bu[2 * e] + wu[0][2 * e] * bflo(u2[e]) + wu[1][2 * e] * bflo(u1[e]) + wu[2][2 * e] * bflo(u0[e]);
;                     const float ub = bu[2 * e + 1] + wu[0][2 * e + 1] * bfhi(u2[e]) + wu[1][2 * e + 1] * bfhi(u1[e]) + wu[2][2 * e + 1] * bfhi(u0[e]);
;                     o[2 * e] = gelu_tanh(ga) * ua; o[2 * e + 1] = gelu_tanh(gb) * ub;
;                 }
;                 v4u w; w.x = cvtpk(o[0], o[1]); w.y = cvtpk(o[2], o[3]); w.z = cvtpk(o[4], o[5]); w.w = cvtpk(o[6], o[7]);
;                 *(v4u*)(hp + (size_t)(n4 + i) * FF) = w;
;                 g2 = g1; g1 = g0; u2 = u1; u1 = u0; }
	v_lshlrev_b32_e32 v94, 16, v65
	v_pk_fma_f32 v[80:81], v[20:21], v[104:105], v[80:81]
	v_lshlrev_b32_e32 v86, 16, v76
	v_and_b32_e32 v87, 0xffff0000, v76
	v_pk_fma_f32 v[80:81], v[36:37], v[86:87], v[80:81]
	v_pk_fma_f32 v[86:87], v[12:13], v[112:113], v[60:61]
	v_mul_f32_e32 v84, 0x3d372713, v80
	v_fma_f32 v84, v80, v84, 1.0
	v_mul_f32_e32 v84, v80, v84
	v_mul_f32_e32 v84, 0xc0135761, v84
	v_exp_f32_e32 v84, v84
	v_pk_fma_f32 v[86:87], v[28:29], v[120:121], v[86:87]
	v_lshlrev_b32_e32 v88, 16, v64
	v_and_b32_e32 v89, 0xffff0000, v64
	v_add_f32_e32 v84, 1.0, v84
	v_pk_fma_f32 v[86:87], v[44:45], v[88:89], v[86:87]
	v_rcp_f32_e32 v88, v84
	v_mul_f32_e32 v84, 0x3d372713, v81
	v_fma_f32 v84, v81, v84, 1.0
	v_mul_f32_e32 v84, v81, v84
	v_mul_f32_e32 v84, 0xc0135761, v84
	v_exp_f32_e32 v84, v84
	v_and_b32_e32 v95, 0xffff0000, v65
	s_mov_b64 s[4:5], 0xb000
	v_lshl_add_u64 v[116:117], v[116:117], 0, s[4:5]
	v_add_f32_e32 v84, 1.0, v84
	v_rcp_f32_e32 v89, v84
	s_mov_b64 s[4:5], 0x16000
	v_lshl_add_u64 v[118:119], v[118:119], 0, s[4:5]
	v_pk_mul_f32 v[80:81], v[80:81], v[88:89]
	s_nop 0
	v_pk_mul_f32 v[80:81], v[86:87], v[80:81]
	v_pk_fma_f32 v[86:87], v[6:7], v[108:109], v[54:55]
	v_lshlrev_b32_e32 v88, 16, v77
	v_pk_fma_f32 v[86:87], v[22:23], v[110:111], v[86:87]
	v_and_b32_e32 v89, 0xffff0000, v77
	v_pk_fma_f32 v[86:87], v[38:39], v[88:89], v[86:87]
	v_pk_fma_f32 v[88:89], v[14:15], v[106:107], v[62:63]
	v_mul_f32_e32 v84, 0x3d372713, v86
	v_fma_f32 v84, v86, v84, 1.0
	v_mul_f32_e32 v84, v86, v84
	v_mul_f32_e32 v84, 0xc0135761, v84
	v_exp_f32_e32 v84, v84
	v_pk_fma_f32 v[88:89], v[30:31], v[122:123], v[88:89]
	v_add_f32_e32 v84, 1.0, v84
	v_pk_fma_f32 v[88:89], v[46:47], v[94:95], v[88:89]
	v_rcp_f32_e32 v94, v84
	v_mul_f32_e32 v84, 0x3d372713, v87
	v_fma_f32 v84, v87, v84, 1.0
	v_mul_f32_e32 v84, v87, v84
	v_mul_f32_e32 v84, 0xc0135761, v84
	v_exp_f32_e32 v84, v84
	s_nop 0
	v_add_f32_e32 v84, 1.0, v84
	v_rcp_f32_e32 v95, v84
	s_nop 0
	v_pk_mul_f32 v[86:87], v[86:87], v[94:95]
	s_nop 0
	v_pk_mul_f32 v[88:89], v[88:89], v[86:87]
	v_pk_fma_f32 v[86:87], v[0:1], v[102:103], v[48:49]
	v_lshlrev_b32_e32 v94, 16, v66
	v_pk_fma_f32 v[86:87], v[16:17], v[90:91], v[86:87]
	v_lshlrev_b32_e32 v90, 16, v78
	v_and_b32_e32 v91, 0xffff0000, v78
	v_pk_fma_f32 v[86:87], v[32:33], v[90:91], v[86:87]
	v_pk_fma_f32 v[90:91], v[8:9], v[98:99], v[56:57]
	v_mul_f32_e32 v84, 0x3d372713, v86
	v_fma_f32 v84, v86, v84, 1.0
	v_mul_f32_e32 v84, v86, v84
	v_mul_f32_e32 v84, 0xc0135761, v84
	v_exp_f32_e32 v84, v84
	v_pk_fma_f32 v[90:91], v[24:25], v[126:127], v[90:91]
	v_and_b32_e32 v95, 0xffff0000, v66
	v_pk_fma_f32 v[90:91], v[40:41], v[94:95], v[90:91]
	v_add_f32_e32 v84, 1.0, v84
	v_rcp_f32_e32 v94, v84
	v_mul_f32_e32 v84, 0x3d372713, v87
	v_fma_f32 v84, v87, v84, 1.0
	v_mul_f32_e32 v84, v87, v84
	v_mul_f32_e32 v84, 0xc0135761, v84
	v_exp_f32_e32 v84, v84
	s_nop 0
	v_add_f32_e32 v84, 1.0, v84
	v_rcp_f32_e32 v95, v84
	s_nop 0
	v_pk_mul_f32 v[86:87], v[86:87], v[94:95]
	s_nop 0
	v_pk_mul_f32 v[90:91], v[90:91], v[86:87]
	v_pk_fma_f32 v[86:87], v[2:3], v[96:97], v[50:51]
	v_lshlrev_b32_e32 v94, 16, v79
	v_pk_fma_f32 v[86:87], v[18:19], v[128:129], v[86:87]
	v_and_b32_e32 v95, 0xffff0000, v79
	v_pk_fma_f32 v[86:87], v[34:35], v[94:95], v[86:87]
	v_lshlrev_b32_e32 v94, 16, v67
	v_mul_f32_e32 v84, 0x3d372713, v86
	v_fma_f32 v84, v86, v84, 1.0
	v_mul_f32_e32 v84, v86, v84
	v_mul_f32_e32 v84, 0xc0135761, v84
	v_exp_f32_e32 v84, v84
	v_and_b32_e32 v95, 0xffff0000, v67
	v_pk_fma_f32 v[92:93], v[42:43], v[94:95], v[92:93]
	v_add_f32_e32 v84, 1.0, v84
	v_rcp_f32_e32 v94, v84
	v_mul_f32_e32 v84, 0x3d372713, v87
	v_fma_f32 v84, v87, v84, 1.0
	v_mul_f32_e32 v84, v87, v84
	v_mul_f32_e32 v84, 0xc0135761, v84
	v_exp_f32_e32 v84, v84
	s_nop 0
	v_add_f32_e32 v84, 1.0, v84
	v_rcp_f32_e32 v95, v84
	s_nop 0
	v_pk_mul_f32 v[86:87], v[86:87], v[94:95]
	s_nop 0
	v_pk_mul_f32 v[92:93], v[92:93], v[86:87]
	v_cvt_pk_bf16_f32 v86, v80, v81
	v_add_co_u32_e32 v80, vcc, 0x37c08000, v82
	v_cvt_pk_bf16_f32 v87, v88, v89
	v_cvt_pk_bf16_f32 v88, v90, v91
	v_cvt_pk_bf16_f32 v89, v92, v93
	v_addc_co_u32_e32 v81, vcc, 0, v83, vcc
	global_store_dwordx4 v[80:81], v[86:89], off offset:1024 sc1
	v_mov_b64_e32 v[82:83], v[78:79]
	v_mov_b64_e32 v[92:93], v[70:71]
	v_mov_b64_e32 v[88:89], v[74:75]
	v_mov_b64_e32 v[96:97], v[66:67]
	v_mov_b64_e32 v[86:87], v[72:73]
	v_mov_b64_e32 v[80:81], v[76:77]
	v_mov_b64_e32 v[90:91], v[68:69]
	v_mov_b64_e32 v[94:95], v[64:65]
	s_cbranch_scc0 .LBB0_102
	v_readlane_b32 s4, v255, 0
	v_readlane_b32 s5, v255, 1
	s_nop 0
	v_add_u32_e32 v138, s4, v138
	s_mov_b32 s4, 0x57fff
	v_cmp_lt_i32_e32 vcc, s4, v138
	s_or_b64 s[56:57], vcc, s[56:57]
	s_andn2_b64 exec, exec, s[56:57]
	s_cbranch_execnz .LBB0_99

; __device__ __forceinline__ void rg_item(LAS unsigned char* lds, int item, const bf16* __restrict__ proj, bf16* __restrict__ mix, const bf16* __restrict__ Gt, ...
;     ...
;     { const bf16* xg = proj + rowbase * INW + 64 * g; v4u rawv[5];
; #pragma unroll
;       for (int i5 = 0; i5 < 5; ++i5) { const int c = tid + 512 * i5, r = c >> 3, t = t0 - 3 + r; rawv[i5] = (v4u){0u, 0u, 0u, 0u};
;           if (c < 259 * 8 && t >= 0) rawv[i5] = *(const v4u*)(xg + (size_t)t * INW + (c & 7) * 8); }
.LBB0_111:
	s_ashr_i32 s6, s97, 6
	s_bfe_u32 s31, s97, 0x20004
	s_and_b32 s5, s97, 15
	s_lshl_b32 s4, s6, 8
	s_mul_i32 s0, s31, 0x1400000
	v_readlane_b32 s8, v252, 4
	v_readlane_b32 s9, v252, 5
	s_add_u32 s0, s8, s0
	s_addc_u32 s1, s9, 0
	s_lshl_b32 s7, s5, 7
	s_add_u32 s0, s0, s7
	s_addc_u32 s1, s1, 0
	s_add_i32 s7, s4, -3
	v_add_u32_e32 v4, s7, v114
	v_cmp_lt_i32_e32 vcc, -1, v4
	v_lshl_add_u64 v[106:107], s[0:1], 0, v[84:85]
	s_and_b64 s[8:9], s[36:37], vcc
	v_mov_b32_e32 v16, v85
	v_mov_b32_e32 v17, v85
	v_mov_b32_e32 v18, v85
	v_mov_b32_e32 v19, v85
	v_mov_b32_e32 v20, v85
	v_mov_b32_e32 v21, v85
	v_mov_b32_e32 v22, v85
	v_mov_b32_e32 v23, v85
	v_mov_b32_e32 v24, v85
	v_mov_b32_e32 v25, v85
	v_mov_b32_e32 v26, v85
	v_mov_b32_e32 v27, v85
	v_mov_b32_e32 v28, v85
	v_mov_b32_e32 v29, v85
	v_mov_b32_e32 v30, v85
	v_mov_b32_e32 v31, v85
	v_mov_b32_e32 v32, v85
	v_mov_b32_e32 v33, v85
	v_mov_b32_e32 v34, v85
	v_mov_b32_e32 v35, v85
	s_movk_i32 s14, 0x3000
	s_and_saveexec_b64 s[0:1], s[8:9]
	s_movk_i32 s8, 0x2800
	v_mad_u64_u32 v[0:1], s[8:9], v4, s8, v[106:107]
	global_load_dwordx4 v[16:19], v[0:1], off
	s_or_b64 exec, exec, s[0:1]
	v_add_u32_e32 v8, s7, v112
	v_cmp_lt_i32_e32 vcc, -1, v8
	s_nop 0
	s_and_b64 s[8:9], s[38:39], vcc
	s_and_saveexec_b64 s[0:1], s[8:9]
	s_movk_i32 s8, 0x2800
	v_mad_u64_u32 v[2:3], s[8:9], v8, s8, v[106:107]
	global_load_dwordx4 v[20:23], v[2:3], off
	s_or_b64 exec, exec, s[0:1]
	v_add_u32_e32 v9, s7, v113
	v_cmp_lt_i32_e32 vcc, -1, v9
	s_nop 0
	s_and_b64 s[8:9], s[40:41], vcc
	s_and_saveexec_b64 s[0:1], s[8:9]
	s_movk_i32 s8, 0x2800
	v_mad_u64_u32 v[4:5], s[8:9], v9, s8, v[106:107]
	global_load_dwordx4 v[24:27], v[4:5], off
	s_or_b64 exec, exec, s[0:1]
	v_add_u32_e32 v10, s7, v115
	v_cmp_lt_i32_e32 vcc, -1, v10
	s_nop 0
	s_and_b64 s[8:9], s[42:43], vcc
	s_and_saveexec_b64 s[0:1], s[8:9]
	s_movk_i32 s8, 0x2800
	v_mad_u64_u32 v[6:7], s[8:9], v10, s8, v[106:107]
	global_load_dwordx4 v[28:31], v[6:7], off
	s_or_b64 exec, exec, s[0:1]
	v_add_u32_e32 v11, s7, v120
	v_cmp_lt_i32_e32 vcc, -1, v11
	s_nop 0
	s_and_b64 s[8:9], s[44:45], vcc
	s_and_saveexec_b64 s[0:1], s[8:9]
	s_movk_i32 s8, 0x2800
	v_mad_u64_u32 v[12:13], s[8:9], v11, s8, v[106:107]
	global_load_dwordx4 v[32:35], v[12:13], off
	s_or_b64 exec, exec, s[0:1]
	s_waitcnt vmcnt(0)

; #define LAS __attribute__((address_space(3)))
; __device__ __forceinline__ void transpose_item(const float* __restrict__ W, int K, int N, bf16* __restrict__ WT, LAS float* scr, int item, int lane) {
;     const int nblk = N / 32, kb = item / nblk, nb = item % nblk, k0 = 64 * kb, n0 = 32 * nb;
;     const float* Wb = W + (size_t)k0 * N + n0; const unsigned loff = (unsigned)(lane >> 5) * (unsigned)N + (unsigned)(lane & 31);
; #pragma unroll 8
;     for (int i = 0; i < 32; ++i) { const int kk = 2 * i + (lane >> 5); scr[kk * 33 + (lane & 31)] = (Wb + (size_t)(2 * i) * N)[loff]; }
;     asm volatile("s_waitcnt lgkmcnt(0)" ::: "memory");
.LBB0_444:
	s_lshl_b32 s28, s11, 12
	s_add_i32 s15, s11, 2
	s_add_i32 s17, s11, 4
	v_lshl_add_u64 v[14:15], s[28:29], 2, v[10:11]
	s_lshl_b32 s28, s15, 12
	s_lshl_b32 s30, s10, 12
	s_mov_b32 s31, s29
	s_add_i32 s49, s11, 6
	v_lshl_add_u64 v[18:19], s[28:29], 2, v[10:11]
	s_lshl_b32 s28, s17, 12
	s_add_i32 s16, s10, 2
	s_add_i32 s48, s10, 4
	s_add_i32 s50, s10, 6
	s_add_i32 s51, s11, 8
	s_add_i32 s52, s10, 8
	s_add_i32 s54, s10, 10
	s_add_i32 s56, s10, 12
	s_add_i32 s58, s10, 14
	v_lshl_add_u64 v[16:17], s[30:31], 2, v[10:11]
	global_load_dword v9, v[14:15], off
	global_load_dword v46, v[16:17], off
	v_lshl_add_u64 v[14:15], s[28:29], 2, v[10:11]
	s_lshl_b32 s28, s49, 12
	s_mov_b32 s35, s29
	s_mov_b32 s37, s29
	s_mov_b32 s39, s29
	s_mov_b32 s41, s29
	s_add_i32 s53, s11, 10
	s_mov_b32 s43, s29
	s_mov_b32 s45, s29
	s_mov_b32 s47, s29
	s_lshl_b32 s34, s16, 12
	s_lshl_b32 s36, s48, 12
	s_lshl_b32 s38, s50, 12
	s_lshl_b32 s40, s52, 12
	s_lshl_b32 s42, s54, 12
	s_lshl_b32 s44, s56, 12
	s_lshl_b32 s46, s58, 12
	v_lshl_add_u64 v[16:17], s[28:29], 2, v[10:11]
	s_lshl_b32 s28, s51, 12
	s_add_i32 s55, s11, 12
	v_lshl_add_u64 v[20:21], s[34:35], 2, v[10:11]
	v_lshl_add_u64 v[22:23], s[36:37], 2, v[10:11]
	v_lshl_add_u64 v[24:25], s[38:39], 2, v[10:11]
	v_lshl_add_u64 v[26:27], s[40:41], 2, v[10:11]
	v_lshl_add_u64 v[28:29], s[42:43], 2, v[10:11]
	v_lshl_add_u64 v[30:31], s[44:45], 2, v[10:11]
	v_lshl_add_u64 v[32:33], s[46:47], 2, v[10:11]
	global_load_dword v47, v[18:19], off
	global_load_dword v48, v[20:21], off
	global_load_dword v49, v[22:23], off
	global_load_dword v50, v[24:25], off
	global_load_dword v51, v[26:27], off
	global_load_dword v52, v[28:29], off
	global_load_dword v53, v[30:31], off
	global_load_dword v54, v[32:33], off
	global_load_dword v55, v[16:17], off
	global_load_dword v56, v[14:15], off
	v_lshl_add_u64 v[14:15], s[28:29], 2, v[10:11]
	s_lshl_b32 s28, s53, 12
	s_add_i32 s57, s11, 14
	v_lshl_add_u64 v[16:17], s[28:29], 2, v[10:11]
	s_lshl_b32 s28, s55, 12
	v_lshl_add_u64 v[18:19], s[28:29], 2, v[10:11]
	s_lshl_b32 s28, s57, 12
	v_lshl_add_u64 v[20:21], s[28:29], 2, v[10:11]
	global_load_dword v57, v[20:21], off
	global_load_dword v58, v[18:19], off
	global_load_dword v59, v[16:17], off
	global_load_dword v60, v[14:15], off
	s_lshl_b32 s13, s10, 1
	s_lshl_b32 s14, s11, 1
	v_or_b32_e32 v16, s13, v1
	v_or_b32_e32 v14, s14, v0
	s_add_i32 s11, s11, 16
	s_add_i32 s10, s10, 16
	s_add_i32 s12, s12, -16
	s_lshl_b32 s13, s16, 1
	s_lshl_b32 s16, s15, 1
	s_lshl_b32 s28, s48, 1
	s_lshl_b32 s17, s17, 1
	s_lshl_b32 s30, s50, 1
	s_lshl_b32 s31, s49, 1
	s_lshl_b32 s34, s52, 1
	s_lshl_b32 s35, s51, 1
	s_lshl_b32 s36, s54, 1
	s_lshl_b32 s37, s53, 1
	s_lshl_b32 s38, s56, 1
	s_lshl_b32 s39, s55, 1
	s_lshl_b32 s40, s58, 1
	s_lshl_b32 s41, s57, 1
	v_mad_u64_u32 v[14:15], s[14:15], v14, s27, v[4:5]
	v_mad_u64_u32 v[16:17], s[14:15], v16, s27, v[4:5]
	v_or_b32_e32 v15, s13, v1
	v_or_b32_e32 v17, s16, v0
	v_or_b32_e32 v24, s28, v1
	v_or_b32_e32 v22, s17, v0
	v_or_b32_e32 v28, s30, v1
	v_or_b32_e32 v26, s31, v0
	v_or_b32_e32 v32, s34, v1
	v_or_b32_e32 v30, s35, v0
	v_or_b32_e32 v36, s36, v1
	v_or_b32_e32 v34, s37, v0
	v_or_b32_e32 v40, s38, v1
	v_or_b32_e32 v38, s39, v0
	v_or_b32_e32 v44, s40, v1
	v_or_b32_e32 v42, s41, v0
	s_cmp_lg_u32 s12, 0
	v_mad_u64_u32 v[18:19], s[14:15], v17, s27, v[4:5]
	v_mad_u64_u32 v[20:21], s[14:15], v15, s27, v[4:5]
	v_mad_u64_u32 v[22:23], s[14:15], v22, s27, v[4:5]
	v_mad_u64_u32 v[24:25], s[14:15], v24, s27, v[4:5]
	v_mad_u64_u32 v[26:27], s[14:15], v26, s27, v[4:5]
	v_mad_u64_u32 v[28:29], s[14:15], v28, s27, v[4:5]
	v_mad_u64_u32 v[30:31], s[14:15], v30, s27, v[4:5]
	v_mad_u64_u32 v[32:33], s[14:15], v32, s27, v[4:5]
	v_mad_u64_u32 v[34:35], s[14:15], v34, s27, v[4:5]
	v_mad_u64_u32 v[36:37], s[14:15], v36, s27, v[4:5]
	v_mad_u64_u32 v[38:39], s[14:15], v38, s27, v[4:5]
	v_mad_u64_u32 v[40:41], s[14:15], v40, s27, v[4:5]
	v_mad_u64_u32 v[42:43], s[14:15], v42, s27, v[4:5]
	v_mad_u64_u32 v[44:45], s[14:15], v44, s27, v[4:5]
	s_waitcnt vmcnt(0)
	ds_write_b32 v14, v9
	ds_write_b32 v16, v46
	ds_write_b32 v18, v47
	ds_write_b32 v20, v48
	ds_write_b32 v22, v56
	ds_write_b32 v24, v49
	ds_write_b32 v26, v55
	ds_write_b32 v28, v50
	ds_write_b32 v30, v60
	ds_write_b32 v32, v51
	ds_write_b32 v34, v59
	ds_write_b32 v36, v52
	ds_write_b32 v38, v58
	ds_write_b32 v40, v53
	ds_write_b32 v42, v57
	ds_write_b32 v44, v54
	s_cbranch_scc1 .LBB0_444
; #define LAS __attribute__((address_space(3)))
; __device__ __forceinline__ unsigned cvtpk(float lo, float hi) { return pg8::cvt_pk_bf16(lo, hi); }
; __device__ __forceinline__ void transpose_item(const float* __restrict__ W, int K, int N, bf16* __restrict__ WT, LAS float* scr, int item, int lane) {
;     ...
;     const int c = lane & 7;
; #pragma unroll
;     for (int j = 0; j < 4; ++j) { const int n = (lane >> 3) + 8 * j; const LAS float* s = scr + (8 * c) * 33 + n;
;         v4u o; o.x = cvtpk(s[0 * 33], s[1 * 33]); o.y = cvtpk(s[2 * 33], s[3 * 33]); o.z = cvtpk(s[4 * 33], s[5 * 33]); o.w = cvtpk(s[6 * 33], s[7 * 33]);
;         *(v4u*)(WT + (size_t)(n0 + n) * K + k0 + 8 * c) = o; }
	s_mul_i32 s11, s0, 0x1600000
	s_waitcnt lgkmcnt(0)
	s_mul_hi_i32 s10, s0, 0x1600000
	s_add_u32 s11, s86, s11
	v_readlane_b32 s12, v253, 43
	ds_read2_b32 v[18:19], v5 offset0:33 offset1:41
	ds_read2_b32 v[20:21], v5 offset1:8
	ds_read2_b32 v[22:23], v5 offset0:66 offset1:74
	ds_read2_b32 v[24:25], v5 offset0:99 offset1:107
	ds_read2_b32 v[26:27], v5 offset0:132 offset1:140
	ds_read2_b32 v[28:29], v5 offset0:165 offset1:173
	ds_read2_b32 v[30:31], v5 offset0:198 offset1:206
	ds_read2_b32 v[32:33], v5 offset0:231 offset1:239
	s_addc_u32 s12, s12, s10
	s_lshl_b32 s9, s9, 1
	s_add_u32 s10, s11, s9
	v_or_b32_e32 v9, s8, v3
	s_addc_u32 s11, s12, 0
	v_lshlrev_b32_e32 v10, 1, v6
	v_mov_b32_e32 v11, v85
	v_mul_u32_u24_e32 v9, 0x1600, v9
	v_lshl_add_u64 v[10:11], s[10:11], 0, v[10:11]
	v_lshlrev_b32_e32 v34, 1, v9
	v_mov_b32_e32 v35, v85
	s_waitcnt lgkmcnt(6)
	v_cvt_pk_bf16_f32 v14, v20, v18
	s_waitcnt lgkmcnt(4)
	v_cvt_pk_bf16_f32 v15, v22, v24
	s_waitcnt lgkmcnt(2)
	v_cvt_pk_bf16_f32 v16, v26, v28
	s_waitcnt lgkmcnt(0)
	v_cvt_pk_bf16_f32 v17, v30, v32
	v_lshl_add_u64 v[34:35], v[10:11], 0, v[34:35]
	global_store_dwordx4 v[34:35], v[14:17], off sc1
	v_or_b32_e32 v9, s8, v7
	v_mul_u32_u24_e32 v9, 0x1600, v9
	v_cvt_pk_bf16_f32 v14, v21, v19
	v_cvt_pk_bf16_f32 v15, v23, v25
	v_cvt_pk_bf16_f32 v16, v27, v29
	v_cvt_pk_bf16_f32 v17, v31, v33
	ds_read2_b32 v[20:21], v5 offset0:16 offset1:24
	ds_read2_b32 v[22:23], v5 offset0:49 offset1:57
	ds_read2_b32 v[24:25], v5 offset0:82 offset1:90
	ds_read2_b32 v[26:27], v5 offset0:115 offset1:123
	ds_read2_b32 v[28:29], v5 offset0:148 offset1:156
	ds_read2_b32 v[30:31], v5 offset0:181 offset1:189
	ds_read2_b32 v[32:33], v5 offset0:214 offset1:222
	ds_read2_b32 v[34:35], v5 offset0:247 offset1:255
	v_lshlrev_b32_e32 v18, 1, v9
	v_mov_b32_e32 v19, v85
	v_or_b32_e32 v9, s8, v12
	v_lshl_add_u64 v[18:19], v[10:11], 0, v[18:19]
	v_mul_u32_u24_e32 v9, 0x1600, v9
	global_store_dwordx4 v[18:19], v[14:17], off sc1
	v_lshlrev_b32_e32 v18, 1, v9
	v_mov_b32_e32 v19, v85
	v_or_b32_e32 v9, s8, v13
	s_waitcnt lgkmcnt(6)
	v_cvt_pk_bf16_f32 v14, v20, v22
	s_waitcnt lgkmcnt(4)
	v_cvt_pk_bf16_f32 v15, v24, v26
	s_waitcnt lgkmcnt(2)
	v_cvt_pk_bf16_f32 v16, v28, v30
	s_waitcnt lgkmcnt(0)
	v_cvt_pk_bf16_f32 v17, v32, v34
	v_lshl_add_u64 v[18:19], v[10:11], 0, v[18:19]
	v_mul_u32_u24_e32 v9, 0x1600, v9
	global_store_dwordx4 v[18:19], v[14:17], off sc1
	v_lshlrev_b32_e32 v18, 1, v9
	v_mov_b32_e32 v19, v85
	v_cvt_pk_bf16_f32 v14, v21, v23
	v_cvt_pk_bf16_f32 v15, v25, v27
	v_cvt_pk_bf16_f32 v16, v29, v31
	v_cvt_pk_bf16_f32 v17, v33, v35
	v_lshl_add_u64 v[10:11], v[10:11], 0, v[18:19]
	global_store_dwordx4 v[10:11], v[14:17], off sc1
	s_waitcnt lgkmcnt(0)
	v_readlane_b32 s50, v254, 61
	v_readlane_b32 s12, v255, 0
	s_mov_b64 s[30:31], 0
	v_readlane_b32 s51, v254, 62
	v_readlane_b32 s13, v255, 1
	s_movk_i32 s17, 0x1000

; #define LAS __attribute__((address_space(3)))
; __device__ __forceinline__ unsigned cvtpk(float lo, float hi) { return pg8::cvt_pk_bf16(lo, hi); }
; __device__ __forceinline__ void transpose_item(const float* __restrict__ W, int K, int N, bf16* __restrict__ WT, LAS float* scr, int item, int lane) {
;     ...
;     for (int i = 0; i < 32; ++i) { const int kk = 2 * i + (lane >> 5); scr[kk * 33 + (lane & 31)] = (Wb + (size_t)(2 * i) * N)[loff]; }
;     asm volatile("s_waitcnt lgkmcnt(0)" ::: "memory");
;     const int c = lane & 7;
; #pragma unroll
;     for (int j = 0; j < 4; ++j) { const int n = (lane >> 3) + 8 * j; const LAS float* s = scr + (8 * c) * 33 + n;
;         v4u o; o.x = cvtpk(s[0 * 33], s[1 * 33]); o.y = cvtpk(s[2 * 33], s[3 * 33]); o.z = cvtpk(s[4 * 33], s[5 * 33]); o.w = cvtpk(s[6 * 33], s[7 * 33]);
;         *(v4u*)(WT + (size_t)(n0 + n) * K + k0 + 8 * c) = o; }
.LBB0_448:
	s_mul_i32 s30, s10, 0x5800
	s_mul_i32 s28, s11, 0x5800
	s_mov_b32 s31, s29
	s_mov_b32 s35, s29
	s_mov_b32 s37, s29
	s_mov_b32 s39, s29
	s_mov_b32 s41, s29
	s_mov_b32 s43, s29
	s_mov_b32 s45, s29
	s_mov_b32 s17, s29
	s_mov_b32 s47, s29
	s_mov_b32 s49, s29
	s_mov_b32 s51, s29
	s_mov_b32 s53, s29
	s_mov_b32 s55, s29
	s_mov_b32 s57, s29
	v_lshl_add_u64 v[14:15], s[28:29], 2, v[10:11]
	s_add_i32 s36, s30, 0xb000
	s_add_i32 s34, s28, 0xb000
	s_add_i32 s40, s30, 0x16000
	s_add_i32 s38, s28, 0x16000
	s_add_i32 s44, s30, 0x21000
	s_add_i32 s42, s28, 0x21000
	s_add_i32 s46, s30, 0x2c000
	s_add_i32 s16, s28, 0x2c000
	s_add_i32 s50, s30, 0x37000
	s_add_i32 s48, s28, 0x37000
	s_add_i32 s54, s30, 0x42000
	s_add_i32 s52, s28, 0x42000
	s_add_i32 s56, s30, 0x4d000
	s_add_i32 s28, s28, 0x4d000
	v_lshl_add_u64 v[16:17], s[30:31], 2, v[10:11]
	v_lshl_add_u64 v[18:19], s[34:35], 2, v[10:11]
	v_lshl_add_u64 v[20:21], s[36:37], 2, v[10:11]
	v_lshl_add_u64 v[22:23], s[38:39], 2, v[10:11]
	v_lshl_add_u64 v[24:25], s[40:41], 2, v[10:11]
	v_lshl_add_u64 v[26:27], s[42:43], 2, v[10:11]
	v_lshl_add_u64 v[28:29], s[44:45], 2, v[10:11]
	v_lshl_add_u64 v[30:31], s[16:17], 2, v[10:11]
	v_lshl_add_u64 v[32:33], s[46:47], 2, v[10:11]
	v_lshl_add_u64 v[34:35], s[48:49], 2, v[10:11]
	v_lshl_add_u64 v[36:37], s[50:51], 2, v[10:11]
	v_lshl_add_u64 v[38:39], s[52:53], 2, v[10:11]
	v_lshl_add_u64 v[40:41], s[54:55], 2, v[10:11]
	v_lshl_add_u64 v[42:43], s[28:29], 2, v[10:11]
	v_lshl_add_u64 v[44:45], s[56:57], 2, v[10:11]
	global_load_dword v9, v[14:15], off
	global_load_dword v46, v[16:17], off
	global_load_dword v47, v[18:19], off
	global_load_dword v48, v[20:21], off
	global_load_dword v49, v[22:23], off
	global_load_dword v50, v[24:25], off
	global_load_dword v51, v[26:27], off
	global_load_dword v52, v[28:29], off
	global_load_dword v53, v[30:31], off
	global_load_dword v54, v[32:33], off
	global_load_dword v55, v[34:35], off
	global_load_dword v56, v[36:37], off
	global_load_dword v57, v[38:39], off
	global_load_dword v58, v[40:41], off
	global_load_dword v59, v[42:43], off
	global_load_dword v60, v[44:45], off
	s_lshl_b32 s13, s10, 1
	s_lshl_b32 s14, s11, 1
	v_or_b32_e32 v16, s13, v1
	v_or_b32_e32 v14, s14, v0
	s_add_i32 s11, s11, 16
	s_add_i32 s10, s10, 16
	s_add_i32 s12, s12, -16
	s_add_i32 s16, s13, 4
	s_add_i32 s17, s14, 4
	s_add_i32 s28, s13, 8
	s_add_i32 s30, s14, 8
	s_add_i32 s31, s13, 12
	s_add_i32 s34, s14, 12
	s_add_i32 s35, s13, 16
	s_add_i32 s36, s14, 16
	s_add_i32 s37, s13, 20
	s_add_i32 s38, s14, 20
	s_add_i32 s39, s13, 24
	s_add_i32 s40, s14, 24
	s_add_i32 s13, s13, 28
	s_add_i32 s41, s14, 28
	v_mad_u64_u32 v[14:15], s[14:15], v14, s27, v[4:5]
	v_mad_u64_u32 v[16:17], s[14:15], v16, s27, v[4:5]
	v_or_b32_e32 v15, s16, v1
	v_or_b32_e32 v17, s17, v0
	v_or_b32_e32 v24, s28, v1
	v_or_b32_e32 v22, s30, v0
	v_or_b32_e32 v28, s31, v1
	v_or_b32_e32 v26, s34, v0
	v_or_b32_e32 v32, s35, v1
	v_or_b32_e32 v30, s36, v0
	v_or_b32_e32 v36, s37, v1
	v_or_b32_e32 v34, s38, v0
	v_or_b32_e32 v40, s39, v1
	v_or_b32_e32 v38, s40, v0
	v_or_b32_e32 v44, s13, v1
	v_or_b32_e32 v42, s41, v0
	s_cmp_lg_u32 s12, 0
	v_mad_u64_u32 v[18:19], s[14:15], v17, s27, v[4:5]
	v_mad_u64_u32 v[20:21], s[14:15], v15, s27, v[4:5]
	v_mad_u64_u32 v[22:23], s[14:15], v22, s27, v[4:5]
	v_mad_u64_u32 v[24:25], s[14:15], v24, s27, v[4:5]
	v_mad_u64_u32 v[26:27], s[14:15], v26, s27, v[4:5]
	v_mad_u64_u32 v[28:29], s[14:15], v28, s27, v[4:5]
	v_mad_u64_u32 v[30:31], s[14:15], v30, s27, v[4:5]
	v_mad_u64_u32 v[32:33], s[14:15], v32, s27, v[4:5]
	v_mad_u64_u32 v[34:35], s[14:15], v34, s27, v[4:5]
	v_mad_u64_u32 v[36:37], s[14:15], v36, s27, v[4:5]
	v_mad_u64_u32 v[38:39], s[14:15], v38, s27, v[4:5]
	v_mad_u64_u32 v[40:41], s[14:15], v40, s27, v[4:5]
	v_mad_u64_u32 v[42:43], s[14:15], v42, s27, v[4:5]
	v_mad_u64_u32 v[44:45], s[14:15], v44, s27, v[4:5]
	s_waitcnt vmcnt(0)
	ds_write_b32 v14, v9
	ds_write_b32 v16, v46
	ds_write_b32 v18, v47
	ds_write_b32 v20, v48
	ds_write_b32 v22, v49
	ds_write_b32 v24, v50
	ds_write_b32 v26, v51
	ds_write_b32 v28, v52
	ds_write_b32 v30, v53
	ds_write_b32 v32, v54
	ds_write_b32 v34, v55
	ds_write_b32 v36, v56
	ds_write_b32 v38, v57
	ds_write_b32 v40, v58
	ds_write_b32 v42, v59
	ds_write_b32 v44, v60
	s_cbranch_scc1 .LBB0_448
	v_readlane_b32 s10, v253, 44
	s_waitcnt lgkmcnt(0)
	s_add_u32 s7, s10, s7
	v_readlane_b32 s10, v253, 45
	ds_read2_b32 v[18:19], v5 offset0:33 offset1:41
	ds_read2_b32 v[20:21], v5 offset1:8
	ds_read2_b32 v[22:23], v5 offset0:66 offset1:74
	ds_read2_b32 v[24:25], v5 offset0:99 offset1:107
	ds_read2_b32 v[26:27], v5 offset0:132 offset1:140
	ds_read2_b32 v[28:29], v5 offset0:165 offset1:173
	ds_read2_b32 v[30:31], v5 offset0:198 offset1:206
	ds_read2_b32 v[32:33], v5 offset0:231 offset1:239
	s_addc_u32 s10, s10, s6
	s_and_b32 s9, 0xffff, s9
	s_lshl_b32 s6, s8, 1
	s_add_u32 s6, s7, s6
	s_addc_u32 s7, s10, 0
	v_lshlrev_b32_e32 v10, 1, v6
	v_mov_b32_e32 v11, v85
	v_or_b32_e32 v9, s9, v3
	v_lshl_add_u64 v[10:11], s[6:7], 0, v[10:11]
	v_lshlrev_b32_e32 v34, 12, v9
	v_mov_b32_e32 v35, v85
	s_waitcnt lgkmcnt(6)
	v_cvt_pk_bf16_f32 v14, v20, v18
	s_waitcnt lgkmcnt(4)
	v_cvt_pk_bf16_f32 v15, v22, v24
	s_waitcnt lgkmcnt(2)
	v_cvt_pk_bf16_f32 v16, v26, v28
	s_waitcnt lgkmcnt(0)
	v_cvt_pk_bf16_f32 v17, v30, v32
	v_lshl_add_u64 v[34:35], v[10:11], 0, v[34:35]
	global_store_dwordx4 v[34:35], v[14:17], off sc1
	v_or_b32_e32 v9, s9, v7
	v_lshlrev_b32_e32 v18, 12, v9
	v_cvt_pk_bf16_f32 v14, v21, v19
	v_cvt_pk_bf16_f32 v15, v23, v25
	v_cvt_pk_bf16_f32 v16, v27, v29
	v_cvt_pk_bf16_f32 v17, v31, v33
	ds_read2_b32 v[20:21], v5 offset0:49 offset1:57
	ds_read2_b32 v[22:23], v5 offset0:16 offset1:24
	ds_read2_b32 v[24:25], v5 offset0:82 offset1:90
	ds_read2_b32 v[26:27], v5 offset0:115 offset1:123
	ds_read2_b32 v[28:29], v5 offset0:148 offset1:156
	ds_read2_b32 v[30:31], v5 offset0:181 offset1:189
	ds_read2_b32 v[32:33], v5 offset0:214 offset1:222
	ds_read2_b32 v[34:35], v5 offset0:247 offset1:255
	v_mov_b32_e32 v19, v85
	v_lshl_add_u64 v[18:19], v[10:11], 0, v[18:19]
	v_or_b32_e32 v9, s9, v12
	global_store_dwordx4 v[18:19], v[14:17], off sc1
	v_lshlrev_b32_e32 v18, 12, v9
	v_mov_b32_e32 v19, v85
	s_waitcnt lgkmcnt(6)
	v_cvt_pk_bf16_f32 v14, v22, v20
	s_waitcnt lgkmcnt(4)
	v_cvt_pk_bf16_f32 v15, v24, v26
	s_waitcnt lgkmcnt(2)
	v_cvt_pk_bf16_f32 v16, v28, v30
	s_waitcnt lgkmcnt(0)
	v_cvt_pk_bf16_f32 v17, v32, v34
	v_lshl_add_u64 v[18:19], v[10:11], 0, v[18:19]
	v_or_b32_e32 v9, s9, v13
	global_store_dwordx4 v[18:19], v[14:17], off sc1
	v_lshlrev_b32_e32 v18, 12, v9
	v_mov_b32_e32 v19, v85
	v_cvt_pk_bf16_f32 v14, v23, v21
	v_cvt_pk_bf16_f32 v15, v25, v27
	v_cvt_pk_bf16_f32 v16, v29, v31
	v_cvt_pk_bf16_f32 v17, v33, v35
	v_lshl_add_u64 v[10:11], v[10:11], 0, v[18:19]
	global_store_dwordx4 v[10:11], v[14:17], off sc1
	s_waitcnt lgkmcnt(0)
	v_readlane_b32 s50, v254, 61
	v_readlane_b32 s12, v255, 0
	s_movk_i32 s17, 0x1000
	v_readlane_b32 s51, v254, 62
	v_readlane_b32 s13, v255, 1

; __device__ __forceinline__ void transpose_item(const float* __restrict__ W, int K, int N, bf16* __restrict__ WT, LAS float* scr, int item, int lane) {
;     ...
;     for (int i = 0; i < 32; ++i) { const int kk = 2 * i + (lane >> 5); scr[kk * 33 + (lane & 31)] = (Wb + (size_t)(2 * i) * N)[loff]; }
;     asm volatile("s_waitcnt lgkmcnt(0)" ::: "memory");
.LBB0_453:
	s_lshl_b32 s28, s8, 12
	s_add_i32 s12, s8, 2
	s_add_i32 s46, s8, 4
	v_lshl_add_u64 v[14:15], s[28:29], 2, v[10:11]
	s_lshl_b32 s28, s12, 12
	s_lshl_b32 s34, s7, 12
	s_mov_b32 s35, s29
	s_add_i32 s48, s8, 6
	v_lshl_add_u64 v[18:19], s[28:29], 2, v[10:11]
	s_lshl_b32 s28, s46, 12
	s_add_i32 s13, s7, 2
	s_add_i32 s47, s7, 4
	s_add_i32 s49, s7, 6
	s_add_i32 s50, s8, 8
	s_add_i32 s51, s7, 8
	s_add_i32 s53, s7, 10
	s_add_i32 s55, s7, 12
	s_add_i32 s57, s7, 14
	v_lshl_add_u64 v[16:17], s[34:35], 2, v[10:11]
	global_load_dword v9, v[14:15], off
	global_load_dword v46, v[16:17], off
	v_lshl_add_u64 v[14:15], s[28:29], 2, v[10:11]
	s_lshl_b32 s28, s48, 12
	s_mov_b32 s37, s29
	s_mov_b32 s39, s29
	s_mov_b32 s41, s29
	s_mov_b32 s15, s29
	s_add_i32 s52, s8, 10
	s_mov_b32 s17, s29
	s_mov_b32 s43, s29
	s_mov_b32 s45, s29
	s_lshl_b32 s36, s13, 12
	s_lshl_b32 s38, s47, 12
	s_lshl_b32 s40, s49, 12
	s_lshl_b32 s14, s51, 12
	s_lshl_b32 s16, s53, 12
	s_lshl_b32 s42, s55, 12
	s_lshl_b32 s44, s57, 12
	v_lshl_add_u64 v[16:17], s[28:29], 2, v[10:11]
	s_lshl_b32 s28, s50, 12
	s_add_i32 s54, s8, 12
	v_lshl_add_u64 v[20:21], s[36:37], 2, v[10:11]
	v_lshl_add_u64 v[22:23], s[38:39], 2, v[10:11]
	v_lshl_add_u64 v[24:25], s[40:41], 2, v[10:11]
	v_lshl_add_u64 v[26:27], s[14:15], 2, v[10:11]
	v_lshl_add_u64 v[28:29], s[16:17], 2, v[10:11]
	v_lshl_add_u64 v[30:31], s[42:43], 2, v[10:11]
	v_lshl_add_u64 v[32:33], s[44:45], 2, v[10:11]
	global_load_dword v47, v[18:19], off
	global_load_dword v48, v[20:21], off
	global_load_dword v49, v[22:23], off
	global_load_dword v50, v[24:25], off
	global_load_dword v51, v[26:27], off
	global_load_dword v52, v[28:29], off
	global_load_dword v53, v[30:31], off
	global_load_dword v54, v[32:33], off
	global_load_dword v55, v[16:17], off
	global_load_dword v56, v[14:15], off
	v_lshl_add_u64 v[14:15], s[28:29], 2, v[10:11]
	s_lshl_b32 s28, s52, 12
	s_add_i32 s56, s8, 14
	v_lshl_add_u64 v[16:17], s[28:29], 2, v[10:11]
	s_lshl_b32 s28, s54, 12
	v_lshl_add_u64 v[18:19], s[28:29], 2, v[10:11]
	s_lshl_b32 s28, s56, 12
	v_lshl_add_u64 v[20:21], s[28:29], 2, v[10:11]
	global_load_dword v57, v[20:21], off
	global_load_dword v58, v[18:19], off
	global_load_dword v59, v[16:17], off
	global_load_dword v60, v[14:15], off
	s_lshl_b32 s10, s7, 1
	s_lshl_b32 s11, s8, 1
	v_or_b32_e32 v16, s10, v1
	v_or_b32_e32 v14, s11, v0
	s_add_i32 s8, s8, 16
	s_add_i32 s7, s7, 16
	s_add_i32 s9, s9, -16
	s_lshl_b32 s13, s13, 1
	s_lshl_b32 s12, s12, 1
	s_lshl_b32 s14, s47, 1
	s_lshl_b32 s15, s46, 1
	s_lshl_b32 s16, s49, 1
	s_lshl_b32 s17, s48, 1
	s_lshl_b32 s28, s51, 1
	s_lshl_b32 s34, s50, 1
	s_lshl_b32 s35, s53, 1
	s_lshl_b32 s36, s52, 1
	s_lshl_b32 s37, s55, 1
	s_lshl_b32 s38, s54, 1
	s_lshl_b32 s39, s57, 1
	s_lshl_b32 s40, s56, 1
	v_mad_u64_u32 v[14:15], s[10:11], v14, s27, v[4:5]
	v_mad_u64_u32 v[16:17], s[10:11], v16, s27, v[4:5]
	v_or_b32_e32 v15, s13, v1
	v_or_b32_e32 v17, s12, v0
	v_or_b32_e32 v24, s14, v1
	v_or_b32_e32 v22, s15, v0
	v_or_b32_e32 v28, s16, v1
	v_or_b32_e32 v26, s17, v0
	v_or_b32_e32 v32, s28, v1
	v_or_b32_e32 v30, s34, v0
	v_or_b32_e32 v36, s35, v1
	v_or_b32_e32 v34, s36, v0
	v_or_b32_e32 v40, s37, v1
	v_or_b32_e32 v38, s38, v0
	v_or_b32_e32 v44, s39, v1
	v_or_b32_e32 v42, s40, v0
	s_cmp_lg_u32 s9, 0
	v_mad_u64_u32 v[18:19], s[10:11], v17, s27, v[4:5]
	v_mad_u64_u32 v[20:21], s[10:11], v15, s27, v[4:5]
	v_mad_u64_u32 v[22:23], s[10:11], v22, s27, v[4:5]
	v_mad_u64_u32 v[24:25], s[10:11], v24, s27, v[4:5]
	v_mad_u64_u32 v[26:27], s[10:11], v26, s27, v[4:5]
	v_mad_u64_u32 v[28:29], s[10:11], v28, s27, v[4:5]
	v_mad_u64_u32 v[30:31], s[10:11], v30, s27, v[4:5]
	v_mad_u64_u32 v[32:33], s[10:11], v32, s27, v[4:5]
	v_mad_u64_u32 v[34:35], s[10:11], v34, s27, v[4:5]
	v_mad_u64_u32 v[36:37], s[10:11], v36, s27, v[4:5]
	v_mad_u64_u32 v[38:39], s[10:11], v38, s27, v[4:5]
	v_mad_u64_u32 v[40:41], s[10:11], v40, s27, v[4:5]
	v_mad_u64_u32 v[42:43], s[10:11], v42, s27, v[4:5]
	v_mad_u64_u32 v[44:45], s[10:11], v44, s27, v[4:5]
	s_waitcnt vmcnt(0)
	ds_write_b32 v14, v9
	ds_write_b32 v16, v46
	ds_write_b32 v18, v47
	ds_write_b32 v20, v48
	ds_write_b32 v22, v56
	ds_write_b32 v24, v49
	ds_write_b32 v26, v55
	ds_write_b32 v28, v50
	ds_write_b32 v30, v60
	ds_write_b32 v32, v51
	ds_write_b32 v34, v59
	ds_write_b32 v36, v52
	ds_write_b32 v38, v58
	ds_write_b32 v40, v53
	ds_write_b32 v42, v57
	ds_write_b32 v44, v54
	s_cbranch_scc1 .LBB0_453
; #define LAS __attribute__((address_space(3)))
; __device__ __forceinline__ unsigned cvtpk(float lo, float hi) { return pg8::cvt_pk_bf16(lo, hi); }
; __device__ __forceinline__ void transpose_item(const float* __restrict__ W, int K, int N, bf16* __restrict__ WT, LAS float* scr, int item, int lane) {
;     ...
;     const int c = lane & 7;
; #pragma unroll
;     for (int j = 0; j < 4; ++j) { const int n = (lane >> 3) + 8 * j; const LAS float* s = scr + (8 * c) * 33 + n;
;         v4u o; o.x = cvtpk(s[0 * 33], s[1 * 33]); o.y = cvtpk(s[2 * 33], s[3 * 33]); o.z = cvtpk(s[4 * 33], s[5 * 33]); o.w = cvtpk(s[6 * 33], s[7 * 33]);
;         *(v4u*)(WT + (size_t)(n0 + n) * K + k0 + 8 * c) = o; }
	s_lshl_b64 s[8:9], s[30:31], 1
	v_readlane_b32 s7, v253, 46
	s_waitcnt lgkmcnt(0)
	s_add_u32 s7, s7, s8
	v_readlane_b32 s8, v253, 47
	ds_read2_b32 v[18:19], v5 offset0:33 offset1:41
	ds_read2_b32 v[20:21], v5 offset1:8
	ds_read2_b32 v[22:23], v5 offset0:66 offset1:74
	ds_read2_b32 v[24:25], v5 offset0:99 offset1:107
	ds_read2_b32 v[26:27], v5 offset0:132 offset1:140
	ds_read2_b32 v[28:29], v5 offset0:165 offset1:173
	ds_read2_b32 v[30:31], v5 offset0:198 offset1:206
	ds_read2_b32 v[32:33], v5 offset0:231 offset1:239
	s_addc_u32 s8, s8, s9
	s_lshl_b32 s6, s6, 1
	s_add_u32 s6, s7, s6
	s_addc_u32 s7, s8, 0
	v_lshlrev_b32_e32 v10, 1, v6
	v_mov_b32_e32 v11, v85
	v_or_b32_e32 v9, s1, v3
	v_lshl_add_u64 v[10:11], s[6:7], 0, v[10:11]
	v_lshlrev_b32_e32 v34, 12, v9
	v_mov_b32_e32 v35, v85
	s_waitcnt lgkmcnt(6)
	v_cvt_pk_bf16_f32 v14, v20, v18
	s_waitcnt lgkmcnt(4)
	v_cvt_pk_bf16_f32 v15, v22, v24
	s_waitcnt lgkmcnt(2)
	v_cvt_pk_bf16_f32 v16, v26, v28
	s_waitcnt lgkmcnt(0)
	v_cvt_pk_bf16_f32 v17, v30, v32
	v_lshl_add_u64 v[34:35], v[10:11], 0, v[34:35]
	global_store_dwordx4 v[34:35], v[14:17], off sc1
	v_or_b32_e32 v9, s1, v7
	v_lshlrev_b32_e32 v18, 12, v9
	v_cvt_pk_bf16_f32 v14, v21, v19
	v_cvt_pk_bf16_f32 v15, v23, v25
	v_cvt_pk_bf16_f32 v16, v27, v29
	v_cvt_pk_bf16_f32 v17, v31, v33
	ds_read2_b32 v[20:21], v5 offset0:49 offset1:57
	ds_read2_b32 v[22:23], v5 offset0:16 offset1:24
	ds_read2_b32 v[24:25], v5 offset0:82 offset1:90
	ds_read2_b32 v[26:27], v5 offset0:115 offset1:123
	ds_read2_b32 v[28:29], v5 offset0:148 offset1:156
	ds_read2_b32 v[30:31], v5 offset0:181 offset1:189
	ds_read2_b32 v[32:33], v5 offset0:214 offset1:222
	ds_read2_b32 v[34:35], v5 offset0:247 offset1:255
	v_mov_b32_e32 v19, v85
	v_lshl_add_u64 v[18:19], v[10:11], 0, v[18:19]
	v_or_b32_e32 v9, s1, v12
	global_store_dwordx4 v[18:19], v[14:17], off sc1
	v_lshlrev_b32_e32 v18, 12, v9
	v_mov_b32_e32 v19, v85
	s_waitcnt lgkmcnt(6)
	v_cvt_pk_bf16_f32 v14, v22, v20
	s_waitcnt lgkmcnt(4)
	v_cvt_pk_bf16_f32 v15, v24, v26
	s_waitcnt lgkmcnt(2)
	v_cvt_pk_bf16_f32 v16, v28, v30
	s_waitcnt lgkmcnt(0)
	v_cvt_pk_bf16_f32 v17, v32, v34
	v_lshl_add_u64 v[18:19], v[10:11], 0, v[18:19]
	v_or_b32_e32 v9, s1, v13
	global_store_dwordx4 v[18:19], v[14:17], off sc1
	v_lshlrev_b32_e32 v18, 12, v9
	v_mov_b32_e32 v19, v85
	v_cvt_pk_bf16_f32 v14, v23, v21
	v_cvt_pk_bf16_f32 v15, v25, v27
	v_cvt_pk_bf16_f32 v16, v29, v31
	v_cvt_pk_bf16_f32 v17, v33, v35
	v_lshl_add_u64 v[10:11], v[10:11], 0, v[18:19]
	global_store_dwordx4 v[10:11], v[14:17], off sc1
	s_waitcnt lgkmcnt(0)
	v_readlane_b32 s50, v254, 61
	v_readlane_b32 s12, v255, 0
	s_movk_i32 s17, 0x1000
	v_readlane_b32 s51, v254, 62
	v_readlane_b32 s13, v255, 1

; #define LAS __attribute__((address_space(3)))
; __device__ __forceinline__ unsigned cvtpk(float lo, float hi) { return pg8::cvt_pk_bf16(lo, hi); }
; __device__ __forceinline__ void transpose_item(const float* __restrict__ W, int K, int N, bf16* __restrict__ WT, LAS float* scr, int item, int lane) {
;     ...
;     for (int i = 0; i < 32; ++i) { const int kk = 2 * i + (lane >> 5); scr[kk * 33 + (lane & 31)] = (Wb + (size_t)(2 * i) * N)[loff]; }
;     asm volatile("s_waitcnt lgkmcnt(0)" ::: "memory");
;     const int c = lane & 7;
; #pragma unroll
;     for (int j = 0; j < 4; ++j) { const int n = (lane >> 3) + 8 * j; const LAS float* s = scr + (8 * c) * 33 + n;
;         v4u o; o.x = cvtpk(s[0 * 33], s[1 * 33]); o.y = cvtpk(s[2 * 33], s[3 * 33]); o.z = cvtpk(s[4 * 33], s[5 * 33]); o.w = cvtpk(s[6 * 33], s[7 * 33]);
;         *(v4u*)(WT + (size_t)(n0 + n) * K + k0 + 8 * c) = o; }
.LBB0_457:
	s_mul_i32 s36, s1, 0x2800
	s_mul_i32 s28, s5, 0x2800
	s_mov_b32 s37, s29
	s_mov_b32 s39, s29
	s_mov_b32 s41, s29
	s_mov_b32 s43, s29
	s_mov_b32 s45, s29
	s_mov_b32 s47, s29
	s_mov_b32 s49, s29
	s_mov_b32 s11, s29
	s_mov_b32 s13, s29
	s_mov_b32 s15, s29
	s_mov_b32 s17, s29
	s_mov_b32 s51, s29
	s_mov_b32 s53, s29
	s_mov_b32 s55, s29
	v_lshl_add_u64 v[14:15], s[28:29], 2, v[10:11]
	s_add_i32 s40, s36, 0x5000
	s_add_i32 s38, s28, 0x5000
	s_add_i32 s44, s36, 0xa000
	s_add_i32 s42, s28, 0xa000
	s_add_i32 s48, s36, 0xf000
	s_add_i32 s46, s28, 0xf000
	s_add_i32 s12, s36, 0x14000
	s_add_i32 s10, s28, 0x14000
	s_add_i32 s16, s36, 0x19000
	s_add_i32 s14, s28, 0x19000
	s_add_i32 s52, s36, 0x1e000
	s_add_i32 s50, s28, 0x1e000
	s_add_i32 s54, s36, 0x23000
	s_add_i32 s28, s28, 0x23000
	v_lshl_add_u64 v[16:17], s[36:37], 2, v[10:11]
	v_lshl_add_u64 v[18:19], s[38:39], 2, v[10:11]
	v_lshl_add_u64 v[20:21], s[40:41], 2, v[10:11]
	v_lshl_add_u64 v[22:23], s[42:43], 2, v[10:11]
	v_lshl_add_u64 v[24:25], s[44:45], 2, v[10:11]
	v_lshl_add_u64 v[26:27], s[46:47], 2, v[10:11]
	v_lshl_add_u64 v[28:29], s[48:49], 2, v[10:11]
	v_lshl_add_u64 v[30:31], s[10:11], 2, v[10:11]
	v_lshl_add_u64 v[32:33], s[12:13], 2, v[10:11]
	v_lshl_add_u64 v[34:35], s[14:15], 2, v[10:11]
	v_lshl_add_u64 v[36:37], s[16:17], 2, v[10:11]
	v_lshl_add_u64 v[38:39], s[50:51], 2, v[10:11]
	v_lshl_add_u64 v[40:41], s[52:53], 2, v[10:11]
	v_lshl_add_u64 v[42:43], s[28:29], 2, v[10:11]
	v_lshl_add_u64 v[44:45], s[54:55], 2, v[10:11]
	global_load_dword v9, v[14:15], off
	global_load_dword v46, v[16:17], off
	global_load_dword v47, v[18:19], off
	global_load_dword v48, v[20:21], off
	global_load_dword v49, v[22:23], off
	global_load_dword v50, v[24:25], off
	global_load_dword v51, v[26:27], off
	global_load_dword v52, v[28:29], off
	global_load_dword v53, v[30:31], off
	global_load_dword v54, v[32:33], off
	global_load_dword v55, v[34:35], off
	global_load_dword v56, v[36:37], off
	global_load_dword v57, v[38:39], off
	global_load_dword v58, v[40:41], off
	global_load_dword v59, v[42:43], off
	global_load_dword v60, v[44:45], off
	s_lshl_b32 s7, s1, 1
	s_lshl_b32 s8, s5, 1
	v_or_b32_e32 v16, s7, v1
	v_or_b32_e32 v14, s8, v0
	s_add_i32 s5, s5, 16
	s_add_i32 s1, s1, 16
	s_add_i32 s6, s6, -16
	s_add_i32 s10, s7, 4
	s_add_i32 s11, s8, 4
	s_add_i32 s12, s7, 8
	s_add_i32 s13, s8, 8
	s_add_i32 s14, s7, 12
	s_add_i32 s15, s8, 12
	s_add_i32 s16, s7, 16
	s_add_i32 s17, s8, 16
	s_add_i32 s28, s7, 20
	s_add_i32 s31, s8, 20
	s_add_i32 s36, s7, 24
	s_add_i32 s37, s8, 24
	s_add_i32 s7, s7, 28
	s_add_i32 s38, s8, 28
	v_mad_u64_u32 v[14:15], s[8:9], v14, s27, v[4:5]
	v_mad_u64_u32 v[16:17], s[8:9], v16, s27, v[4:5]
	v_or_b32_e32 v15, s10, v1
	v_or_b32_e32 v17, s11, v0
	v_or_b32_e32 v24, s12, v1
	v_or_b32_e32 v22, s13, v0
	v_or_b32_e32 v28, s14, v1
	v_or_b32_e32 v26, s15, v0
	v_or_b32_e32 v32, s16, v1
	v_or_b32_e32 v30, s17, v0
	v_or_b32_e32 v36, s28, v1
	v_or_b32_e32 v34, s31, v0
	v_or_b32_e32 v40, s36, v1
	v_or_b32_e32 v38, s37, v0
	v_or_b32_e32 v44, s7, v1
	v_or_b32_e32 v42, s38, v0
	s_cmp_lg_u32 s6, 0
	v_mad_u64_u32 v[18:19], s[8:9], v17, s27, v[4:5]
	v_mad_u64_u32 v[20:21], s[8:9], v15, s27, v[4:5]
	v_mad_u64_u32 v[22:23], s[8:9], v22, s27, v[4:5]
	v_mad_u64_u32 v[24:25], s[8:9], v24, s27, v[4:5]
	v_mad_u64_u32 v[26:27], s[8:9], v26, s27, v[4:5]
	v_mad_u64_u32 v[28:29], s[8:9], v28, s27, v[4:5]
	v_mad_u64_u32 v[30:31], s[8:9], v30, s27, v[4:5]
	v_mad_u64_u32 v[32:33], s[8:9], v32, s27, v[4:5]
	v_mad_u64_u32 v[34:35], s[8:9], v34, s27, v[4:5]
	v_mad_u64_u32 v[36:37], s[8:9], v36, s27, v[4:5]
	v_mad_u64_u32 v[38:39], s[8:9], v38, s27, v[4:5]
	v_mad_u64_u32 v[40:41], s[8:9], v40, s27, v[4:5]
	v_mad_u64_u32 v[42:43], s[8:9], v42, s27, v[4:5]
	v_mad_u64_u32 v[44:45], s[8:9], v44, s27, v[4:5]
	s_waitcnt vmcnt(0)
	ds_write_b32 v14, v9
	ds_write_b32 v16, v46
	ds_write_b32 v18, v47
	ds_write_b32 v20, v48
	ds_write_b32 v22, v49
	ds_write_b32 v24, v50
	ds_write_b32 v26, v51
	ds_write_b32 v28, v52
	ds_write_b32 v30, v53
	ds_write_b32 v32, v54
	ds_write_b32 v34, v55
	ds_write_b32 v36, v56
	ds_write_b32 v38, v57
	ds_write_b32 v40, v58
	ds_write_b32 v42, v59
	ds_write_b32 v44, v60
	s_cbranch_scc1 .LBB0_457
	s_mul_hi_i32 s1, s0, 0x1400000
	s_mul_i32 s0, s0, 0x1400000
	v_readlane_b32 s5, v253, 48
	s_waitcnt lgkmcnt(0)
	s_add_u32 s5, s5, s0
	v_readlane_b32 s0, v253, 49
	ds_read2_b32 v[18:19], v5 offset0:33 offset1:41
	ds_read2_b32 v[20:21], v5 offset1:8
	ds_read2_b32 v[22:23], v5 offset0:66 offset1:74
	ds_read2_b32 v[24:25], v5 offset0:99 offset1:107
	ds_read2_b32 v[26:27], v5 offset0:132 offset1:140
	ds_read2_b32 v[28:29], v5 offset0:165 offset1:173
	ds_read2_b32 v[30:31], v5 offset0:198 offset1:206
	ds_read2_b32 v[32:33], v5 offset0:231 offset1:239
	s_addc_u32 s6, s0, s1
	s_lshl_b64 s[0:1], s[34:35], 1
	s_add_u32 s0, s5, s0
	v_or_b32_e32 v34, s30, v3
	s_addc_u32 s1, s6, s1
	v_lshlrev_b32_e32 v10, 1, v6
	v_mov_b32_e32 v11, v85
	v_ashrrev_i32_e32 v35, 31, v34
	v_lshl_add_u64 v[10:11], s[0:1], 0, v[10:11]
	v_lshlrev_b64 v[34:35], 12, v[34:35]
	s_waitcnt lgkmcnt(6)
	v_cvt_pk_bf16_f32 v14, v20, v18
	s_waitcnt lgkmcnt(4)
	v_cvt_pk_bf16_f32 v15, v22, v24
	s_waitcnt lgkmcnt(2)
	v_cvt_pk_bf16_f32 v16, v26, v28
	s_waitcnt lgkmcnt(0)
	v_cvt_pk_bf16_f32 v17, v30, v32
	v_lshl_add_u64 v[34:35], v[10:11], 0, v[34:35]
	v_or_b32_e32 v18, s30, v7
	global_store_dwordx4 v[34:35], v[14:17], off sc1
	v_readlane_b32 s50, v254, 61
	v_readlane_b32 s12, v255, 0
	v_cvt_pk_bf16_f32 v14, v21, v19
	v_ashrrev_i32_e32 v19, 31, v18
	v_cvt_pk_bf16_f32 v15, v23, v25
	v_cvt_pk_bf16_f32 v16, v27, v29
	v_cvt_pk_bf16_f32 v17, v31, v33
	v_lshlrev_b64 v[18:19], 12, v[18:19]
	ds_read2_b32 v[20:21], v5 offset0:49 offset1:57
	ds_read2_b32 v[22:23], v5 offset0:16 offset1:24
	ds_read2_b32 v[24:25], v5 offset0:82 offset1:90
	ds_read2_b32 v[26:27], v5 offset0:115 offset1:123
	ds_read2_b32 v[28:29], v5 offset0:148 offset1:156
	ds_read2_b32 v[30:31], v5 offset0:181 offset1:189
	ds_read2_b32 v[32:33], v5 offset0:214 offset1:222
	ds_read2_b32 v[34:35], v5 offset0:247 offset1:255
	v_lshl_add_u64 v[18:19], v[10:11], 0, v[18:19]
	global_store_dwordx4 v[18:19], v[14:17], off sc1
	v_or_b32_e32 v18, s30, v12
	v_ashrrev_i32_e32 v19, 31, v18
	v_lshlrev_b64 v[18:19], 12, v[18:19]
	s_waitcnt lgkmcnt(6)
	v_cvt_pk_bf16_f32 v14, v22, v20
	s_waitcnt lgkmcnt(4)
	v_cvt_pk_bf16_f32 v15, v24, v26
	s_waitcnt lgkmcnt(2)
	v_cvt_pk_bf16_f32 v16, v28, v30
	s_waitcnt lgkmcnt(0)
	v_cvt_pk_bf16_f32 v17, v32, v34
	v_lshl_add_u64 v[18:19], v[10:11], 0, v[18:19]
	global_store_dwordx4 v[18:19], v[14:17], off sc1
	v_or_b32_e32 v18, s30, v13
	v_ashrrev_i32_e32 v19, 31, v18
	v_lshlrev_b64 v[18:19], 12, v[18:19]
	v_cvt_pk_bf16_f32 v14, v23, v21
	v_cvt_pk_bf16_f32 v15, v25, v27
	v_cvt_pk_bf16_f32 v16, v29, v31
	v_cvt_pk_bf16_f32 v17, v33, v35
	v_lshl_add_u64 v[10:11], v[10:11], 0, v[18:19]
	global_store_dwordx4 v[10:11], v[14:17], off sc1
	s_waitcnt lgkmcnt(0)
	s_movk_i32 s17, 0x1000
	v_readlane_b32 s51, v254, 62
	v_readlane_b32 s13, v255, 1
	s_branch .LBB0_438
